# gate epilogue: bare v_sqrt_f32 instead of the denorm-scaled sqrt expansion (64 sites), on top of v7
# speedup vs baseline: 1.0516x; 1.0011x over previous
; __device__ __forceinline__ unsigned cvt_pk_bf16(float lo, float hi) { unsigned r; asm volatile("v_cvt_pk_bf16_f32 %0, %1, %2" : "=v"(r) : "v"(lo), "v"(hi)); return r; }
; __device__ __forceinline__ float sigmoidf_(float x) { return 1.f / (1.f + __expf(-x)); }
; __device__ __forceinline__ f32x4 bf4lo(u32x4 r) { return (f32x4){__uint_as_float(r.x << 16), __uint_as_float(r.x & 0xffff0000u), __uint_as_float(r.y << 16), __uint_as_float(r.y & 0xffff0000u)}; }
; __device__ __forceinline__ f32x4 bf4hi(u32x4 r) { return (f32x4){__uint_as_float(r.z << 16), __uint_as_float(r.z & 0xffff0000u), __uint_as_float(r.w << 16), __uint_as_float(r.w & 0xffff0000u)}; }
;     __device__ __forceinline__ void operator()(const f32x4 (&acc)[2][2][4][2], const Unit& u, int wr, int wc, int fr, int fq) const {
;         const int row0 = u.pm * 256 + wr * 64 + fr; const int cb = u.pn * 128 + wc * 32 + 8 * fq;
;         const f32x4 sp0 = *(const f32x4*)(lam + cb), sp1 = *(const f32x4*)(lam + cb + 4), rb0 = *(const f32x4*)(rgb + cb), rb1 = *(const f32x4*)(rgb + cb + 4), ib0 = *(const f32x4*)(igb + cb), ib1 = *(const f32x4*)(igb + cb + 4);
; #pragma unroll
;         for (int ai = 0; ai < 2; ++ai) {
;             f32x4 ucv[4][2];
; #pragma unroll
;             for (int m = 0; m < 4; ++m) { const u32x4 raw = *(const u32x4*)(UCBp + (size_t)(row0 + ai * 128 + m * 16) * 512 + cb); ucv[m][0] = bf4lo(raw); ucv[m][1] = bf4hi(raw); }
; #pragma unroll
;             for (int m = 0; m < 4; ++m)
; #pragma unroll
;                 for (int n = 0; n < 2; ++n) { const size_t off = (size_t)(row0 + ai * 128 + m * 16) * 512 + cb + 4 * n;
;                     const f32x4 uv = ucv[m][n], sp = n ? sp1 : sp0, rb = n ? rb1 : rb0, ib = n ? ib1 : ib0; u32x4 pk;
; #pragma unroll
;                     for (int j = 0; j < 4; ++j) { const float r = sigmoidf_(acc[ai][0][m][n][j] + rb[j]), ig = sigmoidf_(acc[ai][1][m][n][j] + ib[j]);
;                         const float la = sp[j] * r; const float ae = __expf(la); const float om = 1.f - ae; pk[j] = cvt_pk_bf16(om, sqrtf(om * (1.f + ae)) * ig * uv[j]); }
.LBB0_559:
	v_lshl_or_b32 v172, s33, 7, v189
	v_lshl_add_u32 v170, s40, 8, v177
	v_ashrrev_i32_e32 v173, 31, v172
	v_lshlrev_b64 v[168:169], 2, v[172:173]
	v_ashrrev_i32_e32 v171, 31, v170
	v_lshl_add_u64 v[20:21], s[10:11], 0, v[168:169]
	v_lshl_add_u64 v[172:173], v[172:173], 1, s[4:5]
	v_lshlrev_b64 v[174:175], 10, v[170:171]
	global_load_dwordx4 v[16:19], v[20:21], off offset:16
	global_load_dwordx4 v[36:39], v[20:21], off
	v_lshl_add_u64 v[20:21], s[18:19], 0, v[168:169]
	v_lshl_add_u64 v[40:41], s[22:23], 0, v[168:169]
	v_lshl_add_u64 v[174:175], v[172:173], 0, v[174:175]
	global_load_dwordx4 v[24:27], v[20:21], off offset:16
	global_load_dwordx4 v[44:47], v[20:21], off
	s_nop 0
	global_load_dwordx4 v[20:23], v[40:41], off offset:16
	s_nop 0
	global_load_dwordx4 v[40:43], v[40:41], off
	s_waitcnt vmcnt(0)
	v_add_f32_e32 v140, v140, v24
	global_load_dwordx4 v[182:185], v[174:175], off
	v_add_f32_e32 v148, v148, v44
	v_mul_f32_e32 v148, 0xbfb8aa3b, v148
	v_exp_f32_e32 v148, v148
	v_add_f32_e32 v144, v144, v40
	v_mul_f32_e32 v144, 0xbfb8aa3b, v144
	v_exp_f32_e32 v144, v144
	v_add_f32_e32 v148, 1.0, v148
	v_add_f32_e32 v145, v145, v41
	v_mul_f32_e32 v145, 0xbfb8aa3b, v145
	v_add_f32_e32 v144, 1.0, v144
	v_exp_f32_e32 v145, v145
	v_add_f32_e32 v146, v146, v42
	v_mul_f32_e32 v146, 0xbfb8aa3b, v146
	v_exp_f32_e32 v146, v146
	v_add_f32_e32 v145, 1.0, v145
	v_add_f32_e32 v147, v147, v43
	v_mul_f32_e32 v147, 0xbfb8aa3b, v147
	v_add_f32_e32 v146, 1.0, v146
	v_exp_f32_e32 v147, v147
	v_mul_f32_e32 v140, 0xbfb8aa3b, v140
	v_exp_f32_e32 v140, v140
	v_add_f32_e32 v136, v136, v20
	v_add_f32_e32 v147, 1.0, v147
	v_mul_f32_e32 v136, 0xbfb8aa3b, v136
	v_add_f32_e32 v140, 1.0, v140
	v_exp_f32_e32 v136, v136
	v_add_f32_e32 v137, v137, v21
	v_mul_f32_e32 v137, 0xbfb8aa3b, v137
	v_exp_f32_e32 v137, v137
	v_add_f32_e32 v136, 1.0, v136
	v_add_f32_e32 v138, v138, v22
	v_mul_f32_e32 v138, 0xbfb8aa3b, v138
	v_add_f32_e32 v137, 1.0, v137
	v_exp_f32_e32 v138, v138
	v_add_f32_e32 v139, v139, v23
	v_mul_f32_e32 v139, 0xbfb8aa3b, v139
	v_exp_f32_e32 v139, v139
	v_add_f32_e32 v138, 1.0, v138
	v_add_f32_e32 v132, v132, v44
	v_mul_f32_e32 v132, 0xbfb8aa3b, v132
	v_add_f32_e32 v139, 1.0, v139
	v_exp_f32_e32 v132, v132
	v_add_f32_e32 v128, v128, v40
	v_mul_f32_e32 v128, 0xbfb8aa3b, v128
	v_exp_f32_e32 v128, v128
	v_add_f32_e32 v132, 1.0, v132
	v_add_f32_e32 v129, v129, v41
	v_mul_f32_e32 v129, 0xbfb8aa3b, v129
	v_add_f32_e32 v128, 1.0, v128
	v_exp_f32_e32 v129, v129
	v_add_f32_e32 v130, v130, v42
	v_mul_f32_e32 v130, 0xbfb8aa3b, v130
	v_exp_f32_e32 v130, v130
	v_add_f32_e32 v129, 1.0, v129
	v_add_f32_e32 v131, v131, v43
	v_mul_f32_e32 v131, 0xbfb8aa3b, v131
	v_add_f32_e32 v130, 1.0, v130
	v_exp_f32_e32 v131, v131
	v_add_f32_e32 v124, v124, v24
	v_mul_f32_e32 v124, 0xbfb8aa3b, v124
	v_exp_f32_e32 v124, v124
	v_add_f32_e32 v131, 1.0, v131
	v_add_f32_e32 v120, v120, v20
	v_mul_f32_e32 v120, 0xbfb8aa3b, v120
	v_add_f32_e32 v124, 1.0, v124
	v_exp_f32_e32 v120, v120
	v_add_f32_e32 v121, v121, v21
	v_mul_f32_e32 v121, 0xbfb8aa3b, v121
	v_exp_f32_e32 v121, v121
	v_add_f32_e32 v120, 1.0, v120
	v_add_f32_e32 v122, v122, v22
	v_mul_f32_e32 v122, 0xbfb8aa3b, v122
	v_add_f32_e32 v121, 1.0, v121
	v_exp_f32_e32 v122, v122
	v_add_f32_e32 v123, v123, v23
	v_mul_f32_e32 v123, 0xbfb8aa3b, v123
	v_exp_f32_e32 v123, v123
	v_add_f32_e32 v122, 1.0, v122
	v_add_f32_e32 v116, v116, v44
	s_waitcnt vmcnt(0)
	v_lshlrev_b32_e32 v222, 16, v184
	v_and_b32_e32 v221, 0xffff0000, v184
	v_or_b32_e32 v184, 16, v170
	v_lshlrev_b32_e32 v219, 16, v185
	v_and_b32_e32 v218, 0xffff0000, v185
	v_ashrrev_i32_e32 v185, 31, v184
	v_lshlrev_b64 v[174:175], 10, v[184:185]
	v_lshl_add_u64 v[174:175], v[172:173], 0, v[174:175]
	global_load_dwordx4 v[194:197], v[174:175], off
	v_lshlrev_b32_e32 v230, 16, v182
	v_and_b32_e32 v225, 0xffff0000, v182
	v_or_b32_e32 v182, 32, v170
	v_lshlrev_b32_e32 v224, 16, v183
	v_and_b32_e32 v223, 0xffff0000, v183
	v_ashrrev_i32_e32 v183, 31, v182
	v_lshlrev_b64 v[174:175], 10, v[182:183]
	v_lshl_add_u64 v[174:175], v[172:173], 0, v[174:175]
	v_add_f32_e32 v123, 1.0, v123
	v_mul_f32_e32 v116, 0xbfb8aa3b, v116
	v_exp_f32_e32 v116, v116
	v_add_f32_e32 v112, v112, v40
	v_mul_f32_e32 v112, 0xbfb8aa3b, v112
	v_exp_f32_e32 v112, v112
	v_add_f32_e32 v116, 1.0, v116
	v_add_f32_e32 v113, v113, v41
	v_mul_f32_e32 v113, 0xbfb8aa3b, v113
	v_add_f32_e32 v112, 1.0, v112
	v_exp_f32_e32 v113, v113
	v_add_f32_e32 v114, v114, v42
	v_mul_f32_e32 v114, 0xbfb8aa3b, v114
	v_exp_f32_e32 v114, v114
	v_add_f32_e32 v113, 1.0, v113
	v_add_f32_e32 v115, v115, v43
	v_mul_f32_e32 v115, 0xbfb8aa3b, v115
	v_add_f32_e32 v114, 1.0, v114
	v_exp_f32_e32 v115, v115
	v_add_f32_e32 v108, v108, v24
	v_mul_f32_e32 v108, 0xbfb8aa3b, v108
	v_exp_f32_e32 v108, v108
	v_add_f32_e32 v115, 1.0, v115
	v_add_f32_e32 v104, v104, v20
	v_mul_f32_e32 v104, 0xbfb8aa3b, v104
	v_add_f32_e32 v108, 1.0, v108
	v_exp_f32_e32 v104, v104
	v_add_f32_e32 v105, v105, v21
	v_mul_f32_e32 v105, 0xbfb8aa3b, v105
	v_exp_f32_e32 v105, v105
	v_add_f32_e32 v104, 1.0, v104
	v_add_f32_e32 v106, v106, v22
	v_mul_f32_e32 v106, 0xbfb8aa3b, v106
	v_add_f32_e32 v105, 1.0, v105
	v_exp_f32_e32 v106, v106
	v_add_f32_e32 v107, v107, v23
	v_mul_f32_e32 v107, 0xbfb8aa3b, v107
	v_exp_f32_e32 v107, v107
	v_add_f32_e32 v106, 1.0, v106
	v_add_f32_e32 v100, v100, v44
	v_mul_f32_e32 v100, 0xbfb8aa3b, v100
	v_add_f32_e32 v107, 1.0, v107
	v_exp_f32_e32 v100, v100
	v_add_f32_e32 v96, v96, v40
	v_mul_f32_e32 v96, 0xbfb8aa3b, v96
	v_exp_f32_e32 v96, v96
	v_add_f32_e32 v100, 1.0, v100
	v_add_f32_e32 v97, v97, v41
	v_mul_f32_e32 v97, 0xbfb8aa3b, v97
	v_add_f32_e32 v96, 1.0, v96
	v_exp_f32_e32 v97, v97
	v_add_f32_e32 v98, v98, v42
	v_mul_f32_e32 v98, 0xbfb8aa3b, v98
	v_exp_f32_e32 v98, v98
	v_add_f32_e32 v97, 1.0, v97
	v_add_f32_e32 v99, v99, v43
	v_mul_f32_e32 v99, 0xbfb8aa3b, v99
	v_add_f32_e32 v98, 1.0, v98
	v_exp_f32_e32 v99, v99
	v_add_f32_e32 v92, v92, v24
	v_mul_f32_e32 v92, 0xbfb8aa3b, v92
	v_exp_f32_e32 v92, v92
	v_add_f32_e32 v99, 1.0, v99
	v_add_f32_e32 v88, v88, v20
	v_mul_f32_e32 v88, 0xbfb8aa3b, v88
	v_add_f32_e32 v92, 1.0, v92
	v_exp_f32_e32 v88, v88
	v_add_f32_e32 v89, v89, v21
	v_mul_f32_e32 v89, 0xbfb8aa3b, v89
	v_exp_f32_e32 v89, v89
	v_add_f32_e32 v88, 1.0, v88
	s_waitcnt vmcnt(0)
; __device__ __forceinline__ unsigned cvt_pk_bf16(float lo, float hi) { unsigned r; asm volatile("v_cvt_pk_bf16_f32 %0, %1, %2" : "=v"(r) : "v"(lo), "v"(hi)); return r; }
; __device__ __forceinline__ float sigmoidf_(float x) { return 1.f / (1.f + __expf(-x)); }
; __device__ __forceinline__ f32x4 bf4lo(u32x4 r) { return (f32x4){__uint_as_float(r.x << 16), __uint_as_float(r.x & 0xffff0000u), __uint_as_float(r.y << 16), __uint_as_float(r.y & 0xffff0000u)}; }
; __device__ __forceinline__ f32x4 bf4hi(u32x4 r) { return (f32x4){__uint_as_float(r.z << 16), __uint_as_float(r.z & 0xffff0000u), __uint_as_float(r.w << 16), __uint_as_float(r.w & 0xffff0000u)}; }
;     __device__ __forceinline__ void operator()(const f32x4 (&acc)[2][2][4][2], const Unit& u, int wr, int wc, int fr, int fq) const {
;     ...
;             for (int m = 0; m < 4; ++m) { const u32x4 raw = *(const u32x4*)(UCBp + (size_t)(row0 + ai * 128 + m * 16) * 512 + cb); ucv[m][0] = bf4lo(raw); ucv[m][1] = bf4hi(raw); }
; #pragma unroll
;             for (int m = 0; m < 4; ++m)
; #pragma unroll
;                 for (int n = 0; n < 2; ++n) { const size_t off = (size_t)(row0 + ai * 128 + m * 16) * 512 + cb + 4 * n;
;                     const f32x4 uv = ucv[m][n], sp = n ? sp1 : sp0, rb = n ? rb1 : rb0, ib = n ? ib1 : ib0; u32x4 pk;
; #pragma unroll
;                     for (int j = 0; j < 4; ++j) { const float r = sigmoidf_(acc[ai][0][m][n][j] + rb[j]), ig = sigmoidf_(acc[ai][1][m][n][j] + ib[j]);
;                         const float la = sp[j] * r; const float ae = __expf(la); const float om = 1.f - ae; pk[j] = cvt_pk_bf16(om, sqrtf(om * (1.f + ae)) * ig * uv[j]); }
	v_lshlrev_b32_e32 v217, 16, v194
	v_and_b32_e32 v216, 0xffff0000, v194
	v_lshlrev_b32_e32 v215, 16, v195
	v_and_b32_e32 v214, 0xffff0000, v195
	v_lshlrev_b32_e32 v213, 16, v196
	v_and_b32_e32 v212, 0xffff0000, v196
	v_lshlrev_b32_e32 v211, 16, v197
	v_and_b32_e32 v210, 0xffff0000, v197
	global_load_dwordx4 v[194:197], v[174:175], off
	v_or_b32_e32 v174, 48, v170
	v_ashrrev_i32_e32 v175, 31, v174
	v_lshlrev_b64 v[186:187], 10, v[174:175]
	v_lshl_add_u64 v[186:187], v[172:173], 0, v[186:187]
	global_load_dwordx4 v[226:229], v[186:187], off
	v_lshlrev_b64 v[186:187], 11, v[170:171]
	v_add_f32_e32 v89, 1.0, v89
	v_add_f32_e32 v90, v90, v22
	v_mul_f32_e32 v90, 0xbfb8aa3b, v90
	v_exp_f32_e32 v90, v90
	v_add_f32_e32 v91, v91, v23
	v_mul_f32_e32 v91, 0xbfb8aa3b, v91
	v_exp_f32_e32 v91, v91
	v_add_f32_e32 v90, 1.0, v90
	v_add_f32_e32 v84, v84, v44
	v_mul_f32_e32 v84, 0xbfb8aa3b, v84
	v_add_f32_e32 v91, 1.0, v91
	v_exp_f32_e32 v84, v84
	v_add_f32_e32 v80, v80, v40
	v_mul_f32_e32 v80, 0xbfb8aa3b, v80
	v_exp_f32_e32 v80, v80
	v_add_f32_e32 v84, 1.0, v84
	v_add_f32_e32 v81, v81, v41
	v_mul_f32_e32 v81, 0xbfb8aa3b, v81
	v_add_f32_e32 v80, 1.0, v80
	v_exp_f32_e32 v81, v81
	v_add_f32_e32 v82, v82, v42
	v_mul_f32_e32 v82, 0xbfb8aa3b, v82
	v_exp_f32_e32 v82, v82
	v_add_f32_e32 v81, 1.0, v81
	v_add_f32_e32 v83, v83, v43
	v_mul_f32_e32 v83, 0xbfb8aa3b, v83
	v_add_f32_e32 v82, 1.0, v82
	v_exp_f32_e32 v83, v83
	v_add_f32_e32 v76, v76, v24
	v_mul_f32_e32 v76, 0xbfb8aa3b, v76
	v_exp_f32_e32 v76, v76
	v_add_f32_e32 v83, 1.0, v83
	v_add_f32_e32 v72, v72, v20
	v_mul_f32_e32 v72, 0xbfb8aa3b, v72
	v_add_f32_e32 v76, 1.0, v76
	v_exp_f32_e32 v72, v72
	v_add_f32_e32 v73, v73, v21
	v_mul_f32_e32 v73, 0xbfb8aa3b, v73
	v_exp_f32_e32 v73, v73
	v_add_f32_e32 v72, 1.0, v72
	v_add_f32_e32 v74, v74, v22
	v_mul_f32_e32 v74, 0xbfb8aa3b, v74
	v_add_f32_e32 v73, 1.0, v73
	v_exp_f32_e32 v74, v74
	v_add_f32_e32 v75, v75, v23
	v_mul_f32_e32 v75, 0xbfb8aa3b, v75
	v_exp_f32_e32 v75, v75
	v_add_f32_e32 v74, 1.0, v74
	v_add_f32_e32 v68, v68, v44
	v_mul_f32_e32 v68, 0xbfb8aa3b, v68
	v_add_f32_e32 v75, 1.0, v75
	v_exp_f32_e32 v68, v68
	v_add_f32_e32 v64, v64, v40
	v_mul_f32_e32 v64, 0xbfb8aa3b, v64
	v_exp_f32_e32 v64, v64
	v_add_f32_e32 v68, 1.0, v68
	v_add_f32_e32 v65, v65, v41
	v_mul_f32_e32 v65, 0xbfb8aa3b, v65
	v_add_f32_e32 v64, 1.0, v64
	v_exp_f32_e32 v65, v65
	v_add_f32_e32 v66, v66, v42
	v_mul_f32_e32 v66, 0xbfb8aa3b, v66
	v_exp_f32_e32 v66, v66
	v_add_f32_e32 v65, 1.0, v65
	v_add_f32_e32 v67, v67, v43
	v_mul_f32_e32 v67, 0xbfb8aa3b, v67
	v_add_f32_e32 v66, 1.0, v66
	v_exp_f32_e32 v67, v67
	v_add_f32_e32 v60, v60, v24
	v_mul_f32_e32 v60, 0xbfb8aa3b, v60
	v_exp_f32_e32 v60, v60
	s_waitcnt vmcnt(0)
	v_lshlrev_b32_e32 v205, 16, v196
	v_and_b32_e32 v204, 0xffff0000, v196
	v_lshlrev_b32_e32 v203, 16, v197
	v_and_b32_e32 v202, 0xffff0000, v197
	v_lshlrev_b32_e32 v209, 16, v194
	v_lshlrev_b32_e32 v201, 16, v226
	v_and_b32_e32 v200, 0xffff0000, v226
	v_lshlrev_b32_e32 v199, 16, v227
	v_and_b32_e32 v198, 0xffff0000, v227
	v_lshlrev_b32_e32 v197, 16, v228
	v_and_b32_e32 v196, 0xffff0000, v228
	v_and_b32_e32 v208, 0xffff0000, v194
	v_lshlrev_b32_e32 v207, 16, v195
	v_and_b32_e32 v206, 0xffff0000, v195
	v_lshlrev_b32_e32 v195, 16, v229
	v_and_b32_e32 v194, 0xffff0000, v229
	v_rcp_f32_e32 v148, v148
	s_nop 0
	v_mul_f32_e32 v148, v36, v148
	v_mul_f32_e32 v148, 0x3fb8aa3b, v148
	v_exp_f32_e32 v148, v148
	v_rcp_f32_e32 v144, v144
	v_sub_f32_e32 v171, 1.0, v148
	v_add_f32_e32 v148, 1.0, v148
	v_mul_f32_e32 v148, v171, v148
	v_add_f32_e32 v67, 1.0, v67
	v_add_f32_e32 v60, 1.0, v60
	v_add_f32_e32 v56, v56, v20
	v_mul_f32_e32 v56, 0xbfb8aa3b, v56
	v_exp_f32_e32 v56, v56
	s_nop 0
	v_add_f32_e32 v56, 1.0, v56
	v_add_f32_e32 v57, v57, v21
	v_mul_f32_e32 v57, 0xbfb8aa3b, v57
	v_exp_f32_e32 v57, v57
	v_sqrt_f32_e32 v148, v148
	s_nop 0
	v_mul_f32_e32 v144, v144, v148
	v_add_f32_e32 v148, v149, v45
	v_mul_f32_e32 v148, 0xbfb8aa3b, v148
	v_exp_f32_e32 v148, v148
	v_mul_f32_e32 v144, v144, v230
	v_cvt_pk_bf16_f32 v144, v171, v144
	v_add_f32_e32 v57, 1.0, v57
	v_add_f32_e32 v148, 1.0, v148
	v_add_f32_e32 v58, v58, v22
	v_mul_f32_e32 v58, 0xbfb8aa3b, v58
	v_exp_f32_e32 v58, v58
	v_rcp_f32_e32 v148, v148
	s_nop 0
	v_mul_f32_e32 v148, v37, v148
	v_mul_f32_e32 v148, 0x3fb8aa3b, v148
	v_exp_f32_e32 v148, v148
	v_rcp_f32_e32 v145, v145
	v_sub_f32_e32 v149, 1.0, v148
	v_add_f32_e32 v148, 1.0, v148
	v_mul_f32_e32 v148, v149, v148
	v_add_f32_e32 v58, 1.0, v58
	v_add_f32_e32 v59, v59, v23
	v_mul_f32_e32 v59, 0xbfb8aa3b, v59
	v_exp_f32_e32 v59, v59
	s_nop 0
	v_add_f32_e32 v59, 1.0, v59
	v_add_f32_e32 v52, v52, v44
	v_mul_f32_e32 v52, 0xbfb8aa3b, v52
	v_exp_f32_e32 v52, v52
	v_add_f32_e32 v48, v48, v40
	v_sqrt_f32_e32 v148, v148
	s_nop 0
	v_mul_f32_e32 v145, v145, v148
	v_add_f32_e32 v148, v150, v46
	v_mul_f32_e32 v148, 0xbfb8aa3b, v148
	v_exp_f32_e32 v148, v148
	v_mul_f32_e32 v145, v145, v225
	v_cvt_pk_bf16_f32 v145, v149, v145
	v_add_f32_e32 v52, 1.0, v52
	v_add_f32_e32 v148, 1.0, v148
	v_mul_f32_e32 v48, 0xbfb8aa3b, v48
	v_exp_f32_e32 v48, v48
	v_add_f32_e32 v49, v49, v41
	v_rcp_f32_e32 v148, v148
	s_nop 0
	v_mul_f32_e32 v148, v38, v148
	v_mul_f32_e32 v148, 0x3fb8aa3b, v148
	v_exp_f32_e32 v148, v148
	v_rcp_f32_e32 v146, v146
	v_sub_f32_e32 v149, 1.0, v148
	v_add_f32_e32 v148, 1.0, v148
	v_mul_f32_e32 v148, v149, v148
	v_add_f32_e32 v48, 1.0, v48
	v_mul_f32_e32 v49, 0xbfb8aa3b, v49
	v_exp_f32_e32 v49, v49
	v_add_f32_e32 v50, v50, v42
	v_add_f32_e32 v49, 1.0, v49
	v_mul_f32_e32 v50, 0xbfb8aa3b, v50
	v_exp_f32_e32 v50, v50
	s_nop 0
	v_add_f32_e32 v50, 1.0, v50
	v_add_f32_e32 v51, v51, v43
	v_sqrt_f32_e32 v148, v148
; __device__ __forceinline__ unsigned cvt_pk_bf16(float lo, float hi) { unsigned r; asm volatile("v_cvt_pk_bf16_f32 %0, %1, %2" : "=v"(r) : "v"(lo), "v"(hi)); return r; }
; __device__ __forceinline__ float sigmoidf_(float x) { return 1.f / (1.f + __expf(-x)); }
;     __device__ __forceinline__ void operator()(const f32x4 (&acc)[2][2][4][2], const Unit& u, int wr, int wc, int fr, int fq) const {
;     ...
;                 for (int n = 0; n < 2; ++n) { const size_t off = (size_t)(row0 + ai * 128 + m * 16) * 512 + cb + 4 * n;
;                     const f32x4 uv = ucv[m][n], sp = n ? sp1 : sp0, rb = n ? rb1 : rb0, ib = n ? ib1 : ib0; u32x4 pk;
; #pragma unroll
;                     for (int j = 0; j < 4; ++j) { const float r = sigmoidf_(acc[ai][0][m][n][j] + rb[j]), ig = sigmoidf_(acc[ai][1][m][n][j] + ib[j]);
;                         const float la = sp[j] * r; const float ae = __expf(la); const float om = 1.f - ae; pk[j] = cvt_pk_bf16(om, sqrtf(om * (1.f + ae)) * ig * uv[j]); }
;                     *(u32x4*)(AX + off) = pk; }
	s_nop 0
	v_mul_f32_e32 v146, v146, v148
	v_add_f32_e32 v148, v151, v47
	v_mul_f32_e32 v148, 0xbfb8aa3b, v148
	v_exp_f32_e32 v148, v148
	v_mul_f32_e32 v146, v146, v224
	v_cvt_pk_bf16_f32 v146, v149, v146
	v_mul_f32_e32 v51, 0xbfb8aa3b, v51
	v_add_f32_e32 v148, 1.0, v148
	v_exp_f32_e32 v51, v51
	v_add_f32_e32 v32, v32, v24
	v_mul_f32_e32 v32, 0xbfb8aa3b, v32
	v_rcp_f32_e32 v148, v148
	s_nop 0
	v_mul_f32_e32 v148, v39, v148
	v_mul_f32_e32 v148, 0x3fb8aa3b, v148
	v_exp_f32_e32 v148, v148
	v_rcp_f32_e32 v147, v147
	v_sub_f32_e32 v149, 1.0, v148
	v_add_f32_e32 v148, 1.0, v148
	v_mul_f32_e32 v148, v149, v148
	v_add_f32_e32 v51, 1.0, v51
	v_exp_f32_e32 v32, v32
	v_add_f32_e32 v28, v28, v20
	v_mul_f32_e32 v28, 0xbfb8aa3b, v28
	v_add_f32_e32 v32, 1.0, v32
	v_exp_f32_e32 v28, v28
	v_add_f32_e32 v29, v29, v21
	v_add_f32_e32 v28, 1.0, v28
	v_mul_f32_e32 v29, 0xbfb8aa3b, v29
	v_sqrt_f32_e32 v148, v148
	s_nop 0
	v_mul_f32_e32 v147, v147, v148
	v_mul_f32_e32 v147, v147, v223
	v_cvt_pk_bf16_f32 v147, v149, v147
	v_lshl_add_u64 v[148:149], s[12:13], 0, v[186:187]
	v_lshl_add_u64 v[148:149], v[148:149], 0, v[168:169]
	global_store_dwordx4 v[148:149], v[144:147], off
	v_exp_f32_e32 v29, v29
	v_add_f32_e32 v30, v30, v22
	v_add_f32_e32 v29, 1.0, v29
	v_mul_f32_e32 v30, 0xbfb8aa3b, v30
	v_exp_f32_e32 v30, v30
	v_rcp_f32_e32 v140, v140
	s_nop 0
	v_mul_f32_e32 v140, v16, v140
	v_mul_f32_e32 v140, 0x3fb8aa3b, v140
	v_exp_f32_e32 v140, v140
	v_rcp_f32_e32 v136, v136
	v_sub_f32_e32 v144, 1.0, v140
	v_add_f32_e32 v140, 1.0, v140
	v_mul_f32_e32 v140, v144, v140
	v_add_f32_e32 v30, 1.0, v30
	v_add_f32_e32 v31, v31, v23
	v_mul_f32_e32 v31, 0xbfb8aa3b, v31
	v_exp_f32_e32 v31, v31
	s_nop 0
	v_add_f32_e32 v31, 1.0, v31
	v_add_f32_e32 v12, v12, v44
	v_mul_f32_e32 v12, 0xbfb8aa3b, v12
	v_exp_f32_e32 v12, v12
	v_add_f32_e32 v8, v8, v40
	v_sqrt_f32_e32 v140, v140
	s_nop 0
	v_mul_f32_e32 v136, v136, v140
	v_add_f32_e32 v140, v141, v25
	v_mul_f32_e32 v140, 0xbfb8aa3b, v140
	v_exp_f32_e32 v140, v140
	v_mul_f32_e32 v136, v136, v222
	v_cvt_pk_bf16_f32 v136, v144, v136
	v_add_f32_e32 v12, 1.0, v12
	v_add_f32_e32 v140, 1.0, v140
	v_mul_f32_e32 v8, 0xbfb8aa3b, v8
	v_exp_f32_e32 v8, v8
	v_add_f32_e32 v9, v9, v41
	v_rcp_f32_e32 v140, v140
	s_nop 0
	v_mul_f32_e32 v140, v17, v140
	v_mul_f32_e32 v140, 0x3fb8aa3b, v140
	v_exp_f32_e32 v140, v140
	v_rcp_f32_e32 v137, v137
	v_sub_f32_e32 v141, 1.0, v140
	v_add_f32_e32 v140, 1.0, v140
	v_mul_f32_e32 v140, v141, v140
	v_add_f32_e32 v8, 1.0, v8
	v_mul_f32_e32 v9, 0xbfb8aa3b, v9
	v_exp_f32_e32 v9, v9
	v_add_f32_e32 v10, v10, v42
	v_add_f32_e32 v9, 1.0, v9
	v_mul_f32_e32 v10, 0xbfb8aa3b, v10
	v_exp_f32_e32 v10, v10
	s_nop 0
	v_add_f32_e32 v10, 1.0, v10
	v_add_f32_e32 v11, v11, v43
	v_sqrt_f32_e32 v140, v140
	s_nop 0
	v_mul_f32_e32 v137, v137, v140
	v_add_f32_e32 v140, v142, v26
	v_mul_f32_e32 v140, 0xbfb8aa3b, v140
	v_exp_f32_e32 v140, v140
	v_mul_f32_e32 v137, v137, v221
	v_cvt_pk_bf16_f32 v137, v141, v137
	v_mul_f32_e32 v11, 0xbfb8aa3b, v11
	v_add_f32_e32 v140, 1.0, v140
	v_exp_f32_e32 v11, v11
	v_add_f32_e32 v4, v4, v24
	v_mul_f32_e32 v4, 0xbfb8aa3b, v4
	v_rcp_f32_e32 v140, v140
	s_nop 0
	v_mul_f32_e32 v140, v18, v140
	v_mul_f32_e32 v140, 0x3fb8aa3b, v140
	v_exp_f32_e32 v140, v140
	v_rcp_f32_e32 v138, v138
	v_sub_f32_e32 v141, 1.0, v140
	v_add_f32_e32 v140, 1.0, v140
	v_mul_f32_e32 v140, v141, v140
	v_add_f32_e32 v11, 1.0, v11
	v_exp_f32_e32 v4, v4
	v_add_f32_e32 v0, v0, v20
	v_mul_f32_e32 v0, 0xbfb8aa3b, v0
	v_add_f32_e32 v4, 1.0, v4
	v_exp_f32_e32 v0, v0
	v_add_f32_e32 v1, v1, v21
	v_add_f32_e32 v0, 1.0, v0
	v_mul_f32_e32 v1, 0xbfb8aa3b, v1
	v_sqrt_f32_e32 v140, v140
	s_nop 0
	v_mul_f32_e32 v138, v138, v140
	v_add_f32_e32 v140, v143, v27
	v_mul_f32_e32 v140, 0xbfb8aa3b, v140
	v_exp_f32_e32 v140, v140
	v_mul_f32_e32 v138, v138, v219
	v_cvt_pk_bf16_f32 v138, v141, v138
	v_exp_f32_e32 v1, v1
	v_add_f32_e32 v140, 1.0, v140
	v_add_f32_e32 v1, 1.0, v1
	v_add_f32_e32 v2, v2, v22
	v_mul_f32_e32 v2, 0xbfb8aa3b, v2
	v_rcp_f32_e32 v140, v140
	s_nop 0
	v_mul_f32_e32 v140, v19, v140
	v_mul_f32_e32 v140, 0x3fb8aa3b, v140
	v_exp_f32_e32 v140, v140
	v_rcp_f32_e32 v139, v139
	v_sub_f32_e32 v141, 1.0, v140
	v_add_f32_e32 v140, 1.0, v140
	v_mul_f32_e32 v140, v141, v140
	v_exp_f32_e32 v2, v2
	v_add_f32_e32 v3, v3, v23
	v_add_f32_e32 v2, 1.0, v2
	v_mul_f32_e32 v3, 0xbfb8aa3b, v3
	v_exp_f32_e32 v3, v3
	s_nop 0
	v_add_f32_e32 v3, 1.0, v3
	s_nop 0
	s_nop 1
	v_sqrt_f32_e32 v140, v140
	s_nop 0
	v_mul_f32_e32 v139, v139, v140
	v_mul_f32_e32 v139, v139, v218
	v_cvt_pk_bf16_f32 v139, v141, v139
	global_store_dwordx4 v[148:149], v[136:139], off offset:16
	s_nop 1
	v_lshlrev_b64 v[136:137], 11, v[184:185]
	v_rcp_f32_e32 v132, v132
	s_nop 0
	v_mul_f32_e32 v132, v36, v132
	v_mul_f32_e32 v132, 0x3fb8aa3b, v132
	v_exp_f32_e32 v132, v132
	v_rcp_f32_e32 v128, v128
	v_sub_f32_e32 v138, 1.0, v132
	v_add_f32_e32 v132, 1.0, v132
	v_mul_f32_e32 v132, v138, v132
	s_nop 0
	s_nop 0
	s_nop 0
	s_nop 1
	s_nop 1
	v_sqrt_f32_e32 v132, v132
	s_nop 0
	v_mul_f32_e32 v128, v128, v132
	v_add_f32_e32 v132, v133, v45
	v_mul_f32_e32 v132, 0xbfb8aa3b, v132
	v_exp_f32_e32 v132, v132
	v_mul_f32_e32 v128, v128, v217
	v_cvt_pk_bf16_f32 v128, v138, v128
	v_add_f32_e32 v132, 1.0, v132
	s_nop 0
	v_rcp_f32_e32 v132, v132
	s_nop 0
	v_mul_f32_e32 v132, v37, v132
	v_mul_f32_e32 v132, 0x3fb8aa3b, v132
	v_exp_f32_e32 v132, v132
	v_rcp_f32_e32 v129, v129
	v_sub_f32_e32 v133, 1.0, v132
	v_add_f32_e32 v132, 1.0, v132
	v_mul_f32_e32 v132, v133, v132
	s_nop 0
	s_nop 0
	s_nop 0
	s_nop 1
	s_nop 1
	v_sqrt_f32_e32 v132, v132
	s_nop 0
	v_mul_f32_e32 v129, v129, v132
	v_add_f32_e32 v132, v134, v46
	v_mul_f32_e32 v132, 0xbfb8aa3b, v132
; __device__ __forceinline__ unsigned cvt_pk_bf16(float lo, float hi) { unsigned r; asm volatile("v_cvt_pk_bf16_f32 %0, %1, %2" : "=v"(r) : "v"(lo), "v"(hi)); return r; }
; __device__ __forceinline__ float sigmoidf_(float x) { return 1.f / (1.f + __expf(-x)); }
;     __device__ __forceinline__ void operator()(const f32x4 (&acc)[2][2][4][2], const Unit& u, int wr, int wc, int fr, int fq) const {
;     ...
;                 for (int n = 0; n < 2; ++n) { const size_t off = (size_t)(row0 + ai * 128 + m * 16) * 512 + cb + 4 * n;
;                     const f32x4 uv = ucv[m][n], sp = n ? sp1 : sp0, rb = n ? rb1 : rb0, ib = n ? ib1 : ib0; u32x4 pk;
; #pragma unroll
;                     for (int j = 0; j < 4; ++j) { const float r = sigmoidf_(acc[ai][0][m][n][j] + rb[j]), ig = sigmoidf_(acc[ai][1][m][n][j] + ib[j]);
;                         const float la = sp[j] * r; const float ae = __expf(la); const float om = 1.f - ae; pk[j] = cvt_pk_bf16(om, sqrtf(om * (1.f + ae)) * ig * uv[j]); }
;                     *(u32x4*)(AX + off) = pk; }
	v_exp_f32_e32 v132, v132
	v_mul_f32_e32 v129, v129, v216
	v_cvt_pk_bf16_f32 v129, v133, v129
	v_add_f32_e32 v132, 1.0, v132
	s_nop 0
	v_rcp_f32_e32 v132, v132
	s_nop 0
	v_mul_f32_e32 v132, v38, v132
	v_mul_f32_e32 v132, 0x3fb8aa3b, v132
	v_exp_f32_e32 v132, v132
	v_rcp_f32_e32 v130, v130
	v_sub_f32_e32 v133, 1.0, v132
	v_add_f32_e32 v132, 1.0, v132
	v_mul_f32_e32 v132, v133, v132
	s_nop 0
	s_nop 0
	s_nop 0
	s_nop 1
	s_nop 1
	v_sqrt_f32_e32 v132, v132
	s_nop 0
	v_mul_f32_e32 v130, v130, v132
	v_add_f32_e32 v132, v135, v47
	v_mul_f32_e32 v132, 0xbfb8aa3b, v132
	v_exp_f32_e32 v132, v132
	v_mul_f32_e32 v130, v130, v215
	v_cvt_pk_bf16_f32 v130, v133, v130
	v_add_f32_e32 v132, 1.0, v132
	s_nop 0
	v_rcp_f32_e32 v132, v132
	s_nop 0
	v_mul_f32_e32 v132, v39, v132
	v_mul_f32_e32 v132, 0x3fb8aa3b, v132
	v_exp_f32_e32 v132, v132
	v_rcp_f32_e32 v131, v131
	v_sub_f32_e32 v133, 1.0, v132
	v_add_f32_e32 v132, 1.0, v132
	v_mul_f32_e32 v132, v133, v132
	s_nop 0
	s_nop 0
	s_nop 0
	s_nop 1
	s_nop 1
	v_sqrt_f32_e32 v132, v132
	s_nop 0
	v_mul_f32_e32 v131, v131, v132
	v_mul_f32_e32 v131, v131, v214
	v_cvt_pk_bf16_f32 v131, v133, v131
	v_lshl_add_u64 v[132:133], s[12:13], 0, v[136:137]
	v_lshl_add_u64 v[132:133], v[132:133], 0, v[168:169]
	global_store_dwordx4 v[132:133], v[128:131], off
	s_nop 1
	s_nop 0
	v_rcp_f32_e32 v124, v124
	s_nop 0
	v_mul_f32_e32 v124, v16, v124
	v_mul_f32_e32 v124, 0x3fb8aa3b, v124
	v_exp_f32_e32 v124, v124
	v_rcp_f32_e32 v120, v120
	v_sub_f32_e32 v128, 1.0, v124
	v_add_f32_e32 v124, 1.0, v124
	v_mul_f32_e32 v124, v128, v124
	s_nop 0
	s_nop 0
	s_nop 0
	s_nop 1
	s_nop 1
	v_sqrt_f32_e32 v124, v124
	s_nop 0
	v_mul_f32_e32 v120, v120, v124
	v_add_f32_e32 v124, v125, v25
	v_mul_f32_e32 v124, 0xbfb8aa3b, v124
	v_exp_f32_e32 v124, v124
	v_mul_f32_e32 v120, v120, v213
	v_cvt_pk_bf16_f32 v120, v128, v120
	v_add_f32_e32 v124, 1.0, v124
	s_nop 0
	v_rcp_f32_e32 v124, v124
	s_nop 0
	v_mul_f32_e32 v124, v17, v124
	v_mul_f32_e32 v124, 0x3fb8aa3b, v124
	v_exp_f32_e32 v124, v124
	v_rcp_f32_e32 v121, v121
	v_sub_f32_e32 v125, 1.0, v124
	v_add_f32_e32 v124, 1.0, v124
	v_mul_f32_e32 v124, v125, v124
	s_nop 0
	s_nop 0
	s_nop 0
	s_nop 1
	s_nop 1
	v_sqrt_f32_e32 v124, v124
	s_nop 0
	v_mul_f32_e32 v121, v121, v124
	v_add_f32_e32 v124, v126, v26
	v_mul_f32_e32 v124, 0xbfb8aa3b, v124
	v_exp_f32_e32 v124, v124
	v_mul_f32_e32 v121, v121, v212
	v_cvt_pk_bf16_f32 v121, v125, v121
	v_add_f32_e32 v124, 1.0, v124
	s_nop 0
	v_rcp_f32_e32 v124, v124
	s_nop 0
	v_mul_f32_e32 v124, v18, v124
	v_mul_f32_e32 v124, 0x3fb8aa3b, v124
	v_exp_f32_e32 v124, v124
	v_rcp_f32_e32 v122, v122
	v_sub_f32_e32 v125, 1.0, v124
	v_add_f32_e32 v124, 1.0, v124
	v_mul_f32_e32 v124, v125, v124
	s_nop 0
	s_nop 0
	s_nop 0
	s_nop 1
	s_nop 1
	v_sqrt_f32_e32 v124, v124
	s_nop 0
	v_mul_f32_e32 v122, v122, v124
	v_add_f32_e32 v124, v127, v27
	v_mul_f32_e32 v124, 0xbfb8aa3b, v124
	v_exp_f32_e32 v124, v124
	v_mul_f32_e32 v122, v122, v211
	v_cvt_pk_bf16_f32 v122, v125, v122
	v_add_f32_e32 v124, 1.0, v124
	s_nop 0
	v_rcp_f32_e32 v124, v124
	s_nop 0
	v_mul_f32_e32 v124, v19, v124
	v_mul_f32_e32 v124, 0x3fb8aa3b, v124
	v_exp_f32_e32 v124, v124
	v_rcp_f32_e32 v123, v123
	v_sub_f32_e32 v125, 1.0, v124
	v_add_f32_e32 v124, 1.0, v124
	v_mul_f32_e32 v124, v125, v124
	s_nop 0
	s_nop 0
	s_nop 0
	s_nop 1
	s_nop 1
	v_sqrt_f32_e32 v124, v124
	s_nop 0
	v_mul_f32_e32 v123, v123, v124
	v_mul_f32_e32 v123, v123, v210
	v_cvt_pk_bf16_f32 v123, v125, v123
	global_store_dwordx4 v[132:133], v[120:123], off offset:16
	v_add_u32_e32 v132, 0x80, v170
	v_ashrrev_i32_e32 v133, 31, v132
	v_lshlrev_b64 v[120:121], 11, v[182:183]
	v_rcp_f32_e32 v116, v116
	s_nop 0
	v_mul_f32_e32 v116, v36, v116
	v_mul_f32_e32 v116, 0x3fb8aa3b, v116
	v_exp_f32_e32 v116, v116
	v_rcp_f32_e32 v112, v112
	v_sub_f32_e32 v122, 1.0, v116
	v_add_f32_e32 v116, 1.0, v116
	v_mul_f32_e32 v116, v122, v116
	s_nop 0
	s_nop 0
	s_nop 0
	s_nop 1
	s_nop 1
	v_sqrt_f32_e32 v116, v116
	s_nop 0
	v_mul_f32_e32 v112, v112, v116
	v_add_f32_e32 v116, v117, v45
	v_mul_f32_e32 v116, 0xbfb8aa3b, v116
	v_exp_f32_e32 v116, v116
	v_mul_f32_e32 v112, v112, v209
	v_cvt_pk_bf16_f32 v112, v122, v112
	v_add_f32_e32 v116, 1.0, v116
	s_nop 0
	v_rcp_f32_e32 v116, v116
	s_nop 0
	v_mul_f32_e32 v116, v37, v116
	v_mul_f32_e32 v116, 0x3fb8aa3b, v116
	v_exp_f32_e32 v116, v116
	v_rcp_f32_e32 v113, v113
	v_sub_f32_e32 v117, 1.0, v116
	v_add_f32_e32 v116, 1.0, v116
	v_mul_f32_e32 v116, v117, v116
	s_nop 0
	s_nop 0
	s_nop 0
	s_nop 1
	s_nop 1
	v_sqrt_f32_e32 v116, v116
	s_nop 0
	v_mul_f32_e32 v113, v113, v116
	v_add_f32_e32 v116, v118, v46
	v_mul_f32_e32 v116, 0xbfb8aa3b, v116
	v_exp_f32_e32 v116, v116
	v_mul_f32_e32 v113, v113, v208
	v_cvt_pk_bf16_f32 v113, v117, v113
	v_add_f32_e32 v116, 1.0, v116
	s_nop 0
	v_rcp_f32_e32 v116, v116
	s_nop 0
	v_mul_f32_e32 v116, v38, v116
	v_mul_f32_e32 v116, 0x3fb8aa3b, v116
	v_exp_f32_e32 v116, v116
	v_rcp_f32_e32 v114, v114
	v_sub_f32_e32 v117, 1.0, v116
	v_add_f32_e32 v116, 1.0, v116
	v_mul_f32_e32 v116, v117, v116
	s_nop 0
	s_nop 0
	s_nop 0
	s_nop 1
	s_nop 1
	v_sqrt_f32_e32 v116, v116
	s_nop 0
	v_mul_f32_e32 v114, v114, v116
	v_add_f32_e32 v116, v119, v47
	v_mul_f32_e32 v116, 0xbfb8aa3b, v116
	v_exp_f32_e32 v116, v116
	v_mul_f32_e32 v114, v114, v207
	v_cvt_pk_bf16_f32 v114, v117, v114
	v_add_f32_e32 v116, 1.0, v116
	s_nop 0
	v_rcp_f32_e32 v116, v116
	s_nop 0
	v_mul_f32_e32 v116, v39, v116
	v_mul_f32_e32 v116, 0x3fb8aa3b, v116
	v_exp_f32_e32 v116, v116
	v_rcp_f32_e32 v115, v115
	v_sub_f32_e32 v117, 1.0, v116
	v_add_f32_e32 v116, 1.0, v116
	v_mul_f32_e32 v116, v117, v116
	s_nop 0
	s_nop 0
	s_nop 0
	s_nop 1
	s_nop 1
	v_sqrt_f32_e32 v116, v116
	s_nop 0
; __device__ __forceinline__ unsigned cvt_pk_bf16(float lo, float hi) { unsigned r; asm volatile("v_cvt_pk_bf16_f32 %0, %1, %2" : "=v"(r) : "v"(lo), "v"(hi)); return r; }
; __device__ __forceinline__ float sigmoidf_(float x) { return 1.f / (1.f + __expf(-x)); }
;     __device__ __forceinline__ void operator()(const f32x4 (&acc)[2][2][4][2], const Unit& u, int wr, int wc, int fr, int fq) const {
;     ...
;                 for (int n = 0; n < 2; ++n) { const size_t off = (size_t)(row0 + ai * 128 + m * 16) * 512 + cb + 4 * n;
;                     const f32x4 uv = ucv[m][n], sp = n ? sp1 : sp0, rb = n ? rb1 : rb0, ib = n ? ib1 : ib0; u32x4 pk;
; #pragma unroll
;                     for (int j = 0; j < 4; ++j) { const float r = sigmoidf_(acc[ai][0][m][n][j] + rb[j]), ig = sigmoidf_(acc[ai][1][m][n][j] + ib[j]);
;                         const float la = sp[j] * r; const float ae = __expf(la); const float om = 1.f - ae; pk[j] = cvt_pk_bf16(om, sqrtf(om * (1.f + ae)) * ig * uv[j]); }
;                     *(u32x4*)(AX + off) = pk; }
	v_mul_f32_e32 v115, v115, v116
	v_mul_f32_e32 v115, v115, v206
	v_cvt_pk_bf16_f32 v115, v117, v115
	v_lshl_add_u64 v[116:117], s[12:13], 0, v[120:121]
	v_lshl_add_u64 v[116:117], v[116:117], 0, v[168:169]
	global_store_dwordx4 v[116:117], v[112:115], off
	s_nop 1
	s_nop 0
	v_rcp_f32_e32 v108, v108
	s_nop 0
	v_mul_f32_e32 v108, v16, v108
	v_mul_f32_e32 v108, 0x3fb8aa3b, v108
	v_exp_f32_e32 v108, v108
	v_rcp_f32_e32 v104, v104
	v_sub_f32_e32 v112, 1.0, v108
	v_add_f32_e32 v108, 1.0, v108
	v_mul_f32_e32 v108, v112, v108
	s_nop 0
	s_nop 0
	s_nop 0
	s_nop 1
	s_nop 1
	v_sqrt_f32_e32 v108, v108
	s_nop 0
	v_mul_f32_e32 v104, v104, v108
	v_add_f32_e32 v108, v109, v25
	v_mul_f32_e32 v108, 0xbfb8aa3b, v108
	v_exp_f32_e32 v108, v108
	v_mul_f32_e32 v104, v104, v205
	v_cvt_pk_bf16_f32 v104, v112, v104
	v_add_f32_e32 v108, 1.0, v108
	s_nop 0
	v_rcp_f32_e32 v108, v108
	s_nop 0
	v_mul_f32_e32 v108, v17, v108
	v_mul_f32_e32 v108, 0x3fb8aa3b, v108
	v_exp_f32_e32 v108, v108
	v_rcp_f32_e32 v105, v105
	v_sub_f32_e32 v109, 1.0, v108
	v_add_f32_e32 v108, 1.0, v108
	v_mul_f32_e32 v108, v109, v108
	s_nop 0
	s_nop 0
	s_nop 0
	s_nop 1
	s_nop 1
	v_sqrt_f32_e32 v108, v108
	s_nop 0
	v_mul_f32_e32 v105, v105, v108
	v_add_f32_e32 v108, v110, v26
	v_mul_f32_e32 v108, 0xbfb8aa3b, v108
	v_exp_f32_e32 v108, v108
	v_mul_f32_e32 v105, v105, v204
	v_cvt_pk_bf16_f32 v105, v109, v105
	v_add_f32_e32 v108, 1.0, v108
	s_nop 0
	v_rcp_f32_e32 v108, v108
	s_nop 0
	v_mul_f32_e32 v108, v18, v108
	v_mul_f32_e32 v108, 0x3fb8aa3b, v108
	v_exp_f32_e32 v108, v108
	v_rcp_f32_e32 v106, v106
	v_sub_f32_e32 v109, 1.0, v108
	v_add_f32_e32 v108, 1.0, v108
	v_mul_f32_e32 v108, v109, v108
	s_nop 0
	s_nop 0
	s_nop 0
	s_nop 1
	s_nop 1
	v_sqrt_f32_e32 v108, v108
	s_nop 0
	v_mul_f32_e32 v106, v106, v108
	v_add_f32_e32 v108, v111, v27
	v_mul_f32_e32 v108, 0xbfb8aa3b, v108
	v_exp_f32_e32 v108, v108
	v_mul_f32_e32 v106, v106, v203
	v_cvt_pk_bf16_f32 v106, v109, v106
	v_add_f32_e32 v108, 1.0, v108
	s_nop 0
	v_rcp_f32_e32 v108, v108
	s_nop 0
	v_mul_f32_e32 v108, v19, v108
	v_mul_f32_e32 v108, 0x3fb8aa3b, v108
	v_exp_f32_e32 v108, v108
	v_rcp_f32_e32 v107, v107
	v_sub_f32_e32 v109, 1.0, v108
	v_add_f32_e32 v108, 1.0, v108
	v_mul_f32_e32 v108, v109, v108
	s_nop 0
	s_nop 0
	s_nop 0
	s_nop 1
	s_nop 1
	v_sqrt_f32_e32 v108, v108
	s_nop 0
	v_mul_f32_e32 v107, v107, v108
	v_mul_f32_e32 v107, v107, v202
	v_cvt_pk_bf16_f32 v107, v109, v107
	global_store_dwordx4 v[116:117], v[104:107], off offset:16
	s_nop 1
	v_lshlrev_b64 v[104:105], 11, v[174:175]
	v_rcp_f32_e32 v100, v100
	s_nop 0
	v_mul_f32_e32 v100, v36, v100
	v_mul_f32_e32 v100, 0x3fb8aa3b, v100
	v_exp_f32_e32 v100, v100
	v_rcp_f32_e32 v96, v96
	v_sub_f32_e32 v106, 1.0, v100
	v_add_f32_e32 v100, 1.0, v100
	v_mul_f32_e32 v100, v106, v100
	s_nop 0
	s_nop 0
	s_nop 0
	s_nop 1
	s_nop 1
	v_sqrt_f32_e32 v100, v100
	s_nop 0
	v_mul_f32_e32 v96, v96, v100
	v_add_f32_e32 v100, v101, v45
	v_mul_f32_e32 v100, 0xbfb8aa3b, v100
	v_exp_f32_e32 v100, v100
	v_mul_f32_e32 v96, v96, v201
	v_cvt_pk_bf16_f32 v96, v106, v96
	v_add_f32_e32 v100, 1.0, v100
	s_nop 0
	v_rcp_f32_e32 v100, v100
	s_nop 0
	v_mul_f32_e32 v100, v37, v100
	v_mul_f32_e32 v100, 0x3fb8aa3b, v100
	v_exp_f32_e32 v100, v100
	v_rcp_f32_e32 v97, v97
	v_sub_f32_e32 v101, 1.0, v100
	v_add_f32_e32 v100, 1.0, v100
	v_mul_f32_e32 v100, v101, v100
	s_nop 0
	s_nop 0
	s_nop 0
	s_nop 1
	s_nop 1
	v_sqrt_f32_e32 v100, v100
	s_nop 0
	v_mul_f32_e32 v97, v97, v100
	v_add_f32_e32 v100, v102, v46
	v_mul_f32_e32 v100, 0xbfb8aa3b, v100
	v_exp_f32_e32 v100, v100
	v_mul_f32_e32 v97, v97, v200
	v_cvt_pk_bf16_f32 v97, v101, v97
	v_add_f32_e32 v100, 1.0, v100
	s_nop 0
	v_rcp_f32_e32 v100, v100
	s_nop 0
	v_mul_f32_e32 v100, v38, v100
	v_mul_f32_e32 v100, 0x3fb8aa3b, v100
	v_exp_f32_e32 v100, v100
	v_rcp_f32_e32 v98, v98
	v_sub_f32_e32 v101, 1.0, v100
	v_add_f32_e32 v100, 1.0, v100
	v_mul_f32_e32 v100, v101, v100
	s_nop 0
	s_nop 0
	s_nop 0
	s_nop 1
	s_nop 1
	v_sqrt_f32_e32 v100, v100
	s_nop 0
	v_mul_f32_e32 v98, v98, v100
	v_add_f32_e32 v100, v103, v47
	v_mul_f32_e32 v100, 0xbfb8aa3b, v100
	v_exp_f32_e32 v100, v100
	v_mul_f32_e32 v98, v98, v199
	v_cvt_pk_bf16_f32 v98, v101, v98
	v_add_f32_e32 v100, 1.0, v100
	s_nop 0
	v_rcp_f32_e32 v100, v100
	s_nop 0
	v_mul_f32_e32 v100, v39, v100
	v_mul_f32_e32 v100, 0x3fb8aa3b, v100
	v_exp_f32_e32 v100, v100
	v_rcp_f32_e32 v99, v99
	v_sub_f32_e32 v101, 1.0, v100
	v_add_f32_e32 v100, 1.0, v100
	v_mul_f32_e32 v100, v101, v100
	s_nop 0
	s_nop 0
	s_nop 0
	s_nop 1
	s_nop 1
	v_sqrt_f32_e32 v100, v100
	s_nop 0
	v_mul_f32_e32 v99, v99, v100
	v_mul_f32_e32 v99, v99, v198
	v_cvt_pk_bf16_f32 v99, v101, v99
	v_lshl_add_u64 v[100:101], s[12:13], 0, v[104:105]
	v_lshl_add_u64 v[100:101], v[100:101], 0, v[168:169]
	global_store_dwordx4 v[100:101], v[96:99], off
	s_nop 1
	s_nop 0
	v_rcp_f32_e32 v92, v92
	s_nop 0
	v_mul_f32_e32 v92, v16, v92
	v_mul_f32_e32 v92, 0x3fb8aa3b, v92
	v_exp_f32_e32 v92, v92
	v_rcp_f32_e32 v88, v88
	v_sub_f32_e32 v96, 1.0, v92
	v_add_f32_e32 v92, 1.0, v92
	v_mul_f32_e32 v92, v96, v92
	s_nop 0
	s_nop 0
	s_nop 0
	s_nop 1
	s_nop 1
	v_sqrt_f32_e32 v92, v92
	s_nop 0
	v_mul_f32_e32 v88, v88, v92
	v_add_f32_e32 v92, v93, v25
	v_mul_f32_e32 v92, 0xbfb8aa3b, v92
	v_exp_f32_e32 v92, v92
	v_mul_f32_e32 v88, v88, v197
	v_cvt_pk_bf16_f32 v88, v96, v88
	v_add_f32_e32 v92, 1.0, v92
	s_nop 0
	v_rcp_f32_e32 v92, v92
	s_nop 0
	v_mul_f32_e32 v92, v17, v92
	v_mul_f32_e32 v92, 0x3fb8aa3b, v92
	v_exp_f32_e32 v92, v92
	v_rcp_f32_e32 v89, v89
	v_sub_f32_e32 v93, 1.0, v92
	v_add_f32_e32 v92, 1.0, v92
	v_mul_f32_e32 v92, v93, v92
	s_nop 0
	s_nop 0
	s_nop 0
	s_nop 1
	s_nop 1
	v_sqrt_f32_e32 v92, v92
	s_nop 0
; __device__ __forceinline__ unsigned cvt_pk_bf16(float lo, float hi) { unsigned r; asm volatile("v_cvt_pk_bf16_f32 %0, %1, %2" : "=v"(r) : "v"(lo), "v"(hi)); return r; }
; __device__ __forceinline__ float sigmoidf_(float x) { return 1.f / (1.f + __expf(-x)); }
; __device__ __forceinline__ f32x4 bf4lo(u32x4 r) { return (f32x4){__uint_as_float(r.x << 16), __uint_as_float(r.x & 0xffff0000u), __uint_as_float(r.y << 16), __uint_as_float(r.y & 0xffff0000u)}; }
; __device__ __forceinline__ f32x4 bf4hi(u32x4 r) { return (f32x4){__uint_as_float(r.z << 16), __uint_as_float(r.z & 0xffff0000u), __uint_as_float(r.w << 16), __uint_as_float(r.w & 0xffff0000u)}; }
;     __device__ __forceinline__ void operator()(const f32x4 (&acc)[2][2][4][2], const Unit& u, int wr, int wc, int fr, int fq) const {
;     ...
;             for (int m = 0; m < 4; ++m) { const u32x4 raw = *(const u32x4*)(UCBp + (size_t)(row0 + ai * 128 + m * 16) * 512 + cb); ucv[m][0] = bf4lo(raw); ucv[m][1] = bf4hi(raw); }
; #pragma unroll
;             for (int m = 0; m < 4; ++m)
; #pragma unroll
;                 for (int n = 0; n < 2; ++n) { const size_t off = (size_t)(row0 + ai * 128 + m * 16) * 512 + cb + 4 * n;
;                     const f32x4 uv = ucv[m][n], sp = n ? sp1 : sp0, rb = n ? rb1 : rb0, ib = n ? ib1 : ib0; u32x4 pk;
; #pragma unroll
;                     for (int j = 0; j < 4; ++j) { const float r = sigmoidf_(acc[ai][0][m][n][j] + rb[j]), ig = sigmoidf_(acc[ai][1][m][n][j] + ib[j]);
;                         const float la = sp[j] * r; const float ae = __expf(la); const float om = 1.f - ae; pk[j] = cvt_pk_bf16(om, sqrtf(om * (1.f + ae)) * ig * uv[j]); }
;                     *(u32x4*)(AX + off) = pk; }
	v_mul_f32_e32 v89, v89, v92
	v_add_f32_e32 v92, v94, v26
	v_mul_f32_e32 v92, 0xbfb8aa3b, v92
	v_exp_f32_e32 v92, v92
	v_mul_f32_e32 v89, v89, v196
	v_cvt_pk_bf16_f32 v89, v93, v89
	v_add_f32_e32 v92, 1.0, v92
	s_nop 0
	v_rcp_f32_e32 v92, v92
	s_nop 0
	v_mul_f32_e32 v92, v18, v92
	v_mul_f32_e32 v92, 0x3fb8aa3b, v92
	v_exp_f32_e32 v92, v92
	v_rcp_f32_e32 v90, v90
	v_sub_f32_e32 v93, 1.0, v92
	v_add_f32_e32 v92, 1.0, v92
	v_mul_f32_e32 v92, v93, v92
	s_nop 0
	s_nop 0
	s_nop 0
	s_nop 1
	s_nop 1
	v_sqrt_f32_e32 v92, v92
	s_nop 0
	v_mul_f32_e32 v90, v90, v92
	v_add_f32_e32 v92, v95, v27
	v_mul_f32_e32 v92, 0xbfb8aa3b, v92
	v_exp_f32_e32 v92, v92
	v_mul_f32_e32 v90, v90, v195
	v_cvt_pk_bf16_f32 v90, v93, v90
	v_add_f32_e32 v92, 1.0, v92
	s_nop 0
	v_rcp_f32_e32 v92, v92
	s_nop 0
	v_mul_f32_e32 v92, v19, v92
	v_mul_f32_e32 v92, 0x3fb8aa3b, v92
	v_exp_f32_e32 v92, v92
	v_rcp_f32_e32 v91, v91
	v_sub_f32_e32 v93, 1.0, v92
	v_add_f32_e32 v92, 1.0, v92
	v_mul_f32_e32 v92, v93, v92
	s_nop 0
	s_nop 0
	s_nop 0
	s_nop 1
	s_nop 1
	v_sqrt_f32_e32 v92, v92
	s_nop 0
	v_mul_f32_e32 v91, v91, v92
	v_mul_f32_e32 v91, v91, v194
	v_cvt_pk_bf16_f32 v91, v93, v91
	global_store_dwordx4 v[100:101], v[88:91], off offset:16
	v_add_u32_e32 v92, 0x90, v170
	v_ashrrev_i32_e32 v93, 31, v92
	v_lshlrev_b64 v[88:89], 10, v[132:133]
	v_lshl_add_u64 v[88:89], v[172:173], 0, v[88:89]
	global_load_dwordx4 v[88:91], v[88:89], off
	s_waitcnt vmcnt(0)
	v_lshlrev_b32_e32 v127, 16, v88
	v_and_b32_e32 v126, 0xffff0000, v88
	v_lshlrev_b32_e32 v125, 16, v89
	v_and_b32_e32 v124, 0xffff0000, v89
	v_lshlrev_b64 v[88:89], 10, v[92:93]
	v_lshl_add_u64 v[88:89], v[172:173], 0, v[88:89]
	v_lshlrev_b32_e32 v123, 16, v90
	v_and_b32_e32 v122, 0xffff0000, v90
	v_lshlrev_b32_e32 v121, 16, v91
	v_and_b32_e32 v120, 0xffff0000, v91
	global_load_dwordx4 v[88:91], v[88:89], off
	s_waitcnt vmcnt(0)
	v_lshlrev_b32_e32 v115, 16, v90
	v_and_b32_e32 v114, 0xffff0000, v90
	v_add_u32_e32 v90, 0xa0, v170
	v_lshlrev_b32_e32 v113, 16, v91
	v_and_b32_e32 v112, 0xffff0000, v91
	v_ashrrev_i32_e32 v91, 31, v90
	v_lshlrev_b32_e32 v119, 16, v88
	v_and_b32_e32 v118, 0xffff0000, v88
	v_lshlrev_b32_e32 v117, 16, v89
	v_and_b32_e32 v116, 0xffff0000, v89
	v_lshlrev_b64 v[88:89], 10, v[90:91]
	v_lshl_add_u64 v[88:89], v[172:173], 0, v[88:89]
	global_load_dwordx4 v[94:97], v[88:89], off
	v_add_u32_e32 v88, 0xb0, v170
	v_ashrrev_i32_e32 v89, 31, v88
	s_waitcnt vmcnt(0)
	v_lshlrev_b32_e32 v111, 16, v94
	v_and_b32_e32 v110, 0xffff0000, v94
	v_lshlrev_b32_e32 v109, 16, v95
	v_and_b32_e32 v108, 0xffff0000, v95
	v_lshlrev_b64 v[94:95], 10, v[88:89]
	v_lshl_add_u64 v[94:95], v[172:173], 0, v[94:95]
	global_load_dwordx4 v[128:131], v[94:95], off
	v_lshlrev_b32_e32 v107, 16, v96
	v_and_b32_e32 v106, 0xffff0000, v96
	v_lshlrev_b32_e32 v105, 16, v97
	v_and_b32_e32 v104, 0xffff0000, v97
	v_lshlrev_b64 v[94:95], 11, v[132:133]
	s_waitcnt vmcnt(0)
	v_lshlrev_b32_e32 v103, 16, v128
	v_and_b32_e32 v102, 0xffff0000, v128
	v_lshlrev_b32_e32 v101, 16, v129
	v_and_b32_e32 v100, 0xffff0000, v129
	v_lshlrev_b32_e32 v99, 16, v130
	v_and_b32_e32 v98, 0xffff0000, v130
	v_lshlrev_b32_e32 v97, 16, v131
	v_and_b32_e32 v96, 0xffff0000, v131
	v_rcp_f32_e32 v84, v84
	s_nop 0
	v_mul_f32_e32 v84, v36, v84
	v_mul_f32_e32 v84, 0x3fb8aa3b, v84
	v_exp_f32_e32 v84, v84
	v_rcp_f32_e32 v80, v80
	v_sub_f32_e32 v128, 1.0, v84
	v_add_f32_e32 v84, 1.0, v84
	v_mul_f32_e32 v84, v128, v84
	s_nop 0
	s_nop 0
	s_nop 0
	s_nop 1
	s_nop 1
	v_sqrt_f32_e32 v84, v84
	s_nop 0
	v_mul_f32_e32 v80, v80, v84
	v_add_f32_e32 v84, v85, v45
	v_mul_f32_e32 v84, 0xbfb8aa3b, v84
	v_exp_f32_e32 v84, v84
	v_mul_f32_e32 v80, v80, v127
	v_cvt_pk_bf16_f32 v80, v128, v80
	v_add_f32_e32 v84, 1.0, v84
	s_nop 0
	v_rcp_f32_e32 v84, v84
	s_nop 0
	v_mul_f32_e32 v84, v37, v84
	v_mul_f32_e32 v84, 0x3fb8aa3b, v84
	v_exp_f32_e32 v84, v84
	v_rcp_f32_e32 v81, v81
	v_sub_f32_e32 v85, 1.0, v84
	v_add_f32_e32 v84, 1.0, v84
	v_mul_f32_e32 v84, v85, v84
	s_nop 0
	s_nop 0
	s_nop 0
	s_nop 1
	s_nop 1
	v_sqrt_f32_e32 v84, v84
	s_nop 0
	v_mul_f32_e32 v81, v81, v84
	v_add_f32_e32 v84, v86, v46
	v_mul_f32_e32 v84, 0xbfb8aa3b, v84
	v_exp_f32_e32 v84, v84
	v_mul_f32_e32 v81, v81, v126
	v_cvt_pk_bf16_f32 v81, v85, v81
	v_add_f32_e32 v84, 1.0, v84
	s_nop 0
	v_rcp_f32_e32 v84, v84
	s_nop 0
	v_mul_f32_e32 v84, v38, v84
	v_mul_f32_e32 v84, 0x3fb8aa3b, v84
	v_exp_f32_e32 v84, v84
	v_rcp_f32_e32 v82, v82
	v_sub_f32_e32 v85, 1.0, v84
	v_add_f32_e32 v84, 1.0, v84
	v_mul_f32_e32 v84, v85, v84
	s_nop 0
	s_nop 0
	s_nop 0
	s_nop 1
	s_nop 1
	v_sqrt_f32_e32 v84, v84
	s_nop 0
	v_mul_f32_e32 v82, v82, v84
	v_add_f32_e32 v84, v87, v47
	v_mul_f32_e32 v84, 0xbfb8aa3b, v84
	v_exp_f32_e32 v84, v84
	v_mul_f32_e32 v82, v82, v125
	v_cvt_pk_bf16_f32 v82, v85, v82
	v_add_f32_e32 v84, 1.0, v84
	s_nop 0
	v_rcp_f32_e32 v84, v84
	s_nop 0
	v_mul_f32_e32 v84, v39, v84
	v_mul_f32_e32 v84, 0x3fb8aa3b, v84
	v_exp_f32_e32 v84, v84
	v_rcp_f32_e32 v83, v83
	v_sub_f32_e32 v85, 1.0, v84
	v_add_f32_e32 v84, 1.0, v84
	v_mul_f32_e32 v84, v85, v84
	s_nop 0
	s_nop 0
	s_nop 0
	s_nop 1
	s_nop 1
	v_sqrt_f32_e32 v84, v84
	s_nop 0
	v_mul_f32_e32 v83, v83, v84
	v_mul_f32_e32 v83, v83, v124
	v_cvt_pk_bf16_f32 v83, v85, v83
	v_lshl_add_u64 v[84:85], s[12:13], 0, v[94:95]
	v_lshl_add_u64 v[84:85], v[84:85], 0, v[168:169]
	global_store_dwordx4 v[84:85], v[80:83], off
	s_nop 1
	s_nop 0
	v_rcp_f32_e32 v76, v76
	s_nop 0
	v_mul_f32_e32 v76, v16, v76
	v_mul_f32_e32 v76, 0x3fb8aa3b, v76
	v_exp_f32_e32 v76, v76
	v_rcp_f32_e32 v72, v72
	v_sub_f32_e32 v80, 1.0, v76
	v_add_f32_e32 v76, 1.0, v76
	v_mul_f32_e32 v76, v80, v76
	s_nop 0
	s_nop 0
	s_nop 0
	s_nop 1
	s_nop 1
	v_sqrt_f32_e32 v76, v76
; __device__ __forceinline__ unsigned cvt_pk_bf16(float lo, float hi) { unsigned r; asm volatile("v_cvt_pk_bf16_f32 %0, %1, %2" : "=v"(r) : "v"(lo), "v"(hi)); return r; }
; __device__ __forceinline__ float sigmoidf_(float x) { return 1.f / (1.f + __expf(-x)); }
;     __device__ __forceinline__ void operator()(const f32x4 (&acc)[2][2][4][2], const Unit& u, int wr, int wc, int fr, int fq) const {
;     ...
;                 for (int n = 0; n < 2; ++n) { const size_t off = (size_t)(row0 + ai * 128 + m * 16) * 512 + cb + 4 * n;
;                     const f32x4 uv = ucv[m][n], sp = n ? sp1 : sp0, rb = n ? rb1 : rb0, ib = n ? ib1 : ib0; u32x4 pk;
; #pragma unroll
;                     for (int j = 0; j < 4; ++j) { const float r = sigmoidf_(acc[ai][0][m][n][j] + rb[j]), ig = sigmoidf_(acc[ai][1][m][n][j] + ib[j]);
;                         const float la = sp[j] * r; const float ae = __expf(la); const float om = 1.f - ae; pk[j] = cvt_pk_bf16(om, sqrtf(om * (1.f + ae)) * ig * uv[j]); }
;                     *(u32x4*)(AX + off) = pk; }
	s_nop 0
	v_mul_f32_e32 v72, v72, v76
	v_add_f32_e32 v76, v77, v25
	v_mul_f32_e32 v76, 0xbfb8aa3b, v76
	v_exp_f32_e32 v76, v76
	v_mul_f32_e32 v72, v72, v123
	v_cvt_pk_bf16_f32 v72, v80, v72
	v_add_f32_e32 v76, 1.0, v76
	s_nop 0
	v_rcp_f32_e32 v76, v76
	s_nop 0
	v_mul_f32_e32 v76, v17, v76
	v_mul_f32_e32 v76, 0x3fb8aa3b, v76
	v_exp_f32_e32 v76, v76
	v_rcp_f32_e32 v73, v73
	v_sub_f32_e32 v77, 1.0, v76
	v_add_f32_e32 v76, 1.0, v76
	v_mul_f32_e32 v76, v77, v76
	s_nop 0
	s_nop 0
	s_nop 0
	s_nop 1
	s_nop 1
	v_sqrt_f32_e32 v76, v76
	s_nop 0
	v_mul_f32_e32 v73, v73, v76
	v_add_f32_e32 v76, v78, v26
	v_mul_f32_e32 v76, 0xbfb8aa3b, v76
	v_exp_f32_e32 v76, v76
	v_mul_f32_e32 v73, v73, v122
	v_cvt_pk_bf16_f32 v73, v77, v73
	v_add_f32_e32 v76, 1.0, v76
	s_nop 0
	v_rcp_f32_e32 v76, v76
	s_nop 0
	v_mul_f32_e32 v76, v18, v76
	v_mul_f32_e32 v76, 0x3fb8aa3b, v76
	v_exp_f32_e32 v76, v76
	v_rcp_f32_e32 v74, v74
	v_sub_f32_e32 v77, 1.0, v76
	v_add_f32_e32 v76, 1.0, v76
	v_mul_f32_e32 v76, v77, v76
	s_nop 0
	s_nop 0
	s_nop 0
	s_nop 1
	s_nop 1
	v_sqrt_f32_e32 v76, v76
	s_nop 0
	v_mul_f32_e32 v74, v74, v76
	v_add_f32_e32 v76, v79, v27
	v_mul_f32_e32 v76, 0xbfb8aa3b, v76
	v_exp_f32_e32 v76, v76
	v_mul_f32_e32 v74, v74, v121
	v_cvt_pk_bf16_f32 v74, v77, v74
	v_add_f32_e32 v76, 1.0, v76
	s_nop 0
	v_rcp_f32_e32 v76, v76
	s_nop 0
	v_mul_f32_e32 v76, v19, v76
	v_mul_f32_e32 v76, 0x3fb8aa3b, v76
	v_exp_f32_e32 v76, v76
	v_rcp_f32_e32 v75, v75
	v_sub_f32_e32 v77, 1.0, v76
	v_add_f32_e32 v76, 1.0, v76
	v_mul_f32_e32 v76, v77, v76
	s_nop 0
	s_nop 0
	s_nop 0
	s_nop 1
	s_nop 1
	v_sqrt_f32_e32 v76, v76
	s_nop 0
	v_mul_f32_e32 v75, v75, v76
	v_mul_f32_e32 v75, v75, v120
	v_cvt_pk_bf16_f32 v75, v77, v75
	global_store_dwordx4 v[84:85], v[72:75], off offset:16
	s_nop 1
	v_lshlrev_b64 v[72:73], 11, v[92:93]
	v_rcp_f32_e32 v68, v68
	s_nop 0
	v_mul_f32_e32 v68, v36, v68
	v_mul_f32_e32 v68, 0x3fb8aa3b, v68
	v_exp_f32_e32 v68, v68
	v_rcp_f32_e32 v64, v64
	v_sub_f32_e32 v74, 1.0, v68
	v_add_f32_e32 v68, 1.0, v68
	v_mul_f32_e32 v68, v74, v68
	s_nop 0
	s_nop 0
	s_nop 0
	s_nop 1
	s_nop 1
	v_sqrt_f32_e32 v68, v68
	s_nop 0
	v_mul_f32_e32 v64, v64, v68
	v_add_f32_e32 v68, v69, v45
	v_mul_f32_e32 v68, 0xbfb8aa3b, v68
	v_exp_f32_e32 v68, v68
	v_mul_f32_e32 v64, v64, v119
	v_cvt_pk_bf16_f32 v64, v74, v64
	v_add_f32_e32 v68, 1.0, v68
	s_nop 0
	v_rcp_f32_e32 v68, v68
	s_nop 0
	v_mul_f32_e32 v68, v37, v68
	v_mul_f32_e32 v68, 0x3fb8aa3b, v68
	v_exp_f32_e32 v68, v68
	v_rcp_f32_e32 v65, v65
	v_sub_f32_e32 v69, 1.0, v68
	v_add_f32_e32 v68, 1.0, v68
	v_mul_f32_e32 v68, v69, v68
	s_nop 0
	s_nop 0
	s_nop 0
	s_nop 1
	s_nop 1
	v_sqrt_f32_e32 v68, v68
	s_nop 0
	v_mul_f32_e32 v65, v65, v68
	v_add_f32_e32 v68, v70, v46
	v_mul_f32_e32 v68, 0xbfb8aa3b, v68
	v_exp_f32_e32 v68, v68
	v_mul_f32_e32 v65, v65, v118
	v_cvt_pk_bf16_f32 v65, v69, v65
	v_add_f32_e32 v68, 1.0, v68
	s_nop 0
	v_rcp_f32_e32 v68, v68
	s_nop 0
	v_mul_f32_e32 v68, v38, v68
	v_mul_f32_e32 v68, 0x3fb8aa3b, v68
	v_exp_f32_e32 v68, v68
	v_rcp_f32_e32 v66, v66
	v_sub_f32_e32 v69, 1.0, v68
	v_add_f32_e32 v68, 1.0, v68
	v_mul_f32_e32 v68, v69, v68
	s_nop 0
	s_nop 0
	s_nop 0
	s_nop 1
	s_nop 1
	v_sqrt_f32_e32 v68, v68
	s_nop 0
	v_mul_f32_e32 v66, v66, v68
	v_add_f32_e32 v68, v71, v47
	v_mul_f32_e32 v68, 0xbfb8aa3b, v68
	v_exp_f32_e32 v68, v68
	v_mul_f32_e32 v66, v66, v117
	v_cvt_pk_bf16_f32 v66, v69, v66
	v_add_f32_e32 v68, 1.0, v68
	s_nop 0
	v_rcp_f32_e32 v68, v68
	s_nop 0
	v_mul_f32_e32 v68, v39, v68
	v_mul_f32_e32 v68, 0x3fb8aa3b, v68
	v_exp_f32_e32 v68, v68
	v_rcp_f32_e32 v67, v67
	v_sub_f32_e32 v69, 1.0, v68
	v_add_f32_e32 v68, 1.0, v68
	v_mul_f32_e32 v68, v69, v68
	s_nop 0
	s_nop 0
	s_nop 0
	s_nop 1
	s_nop 1
	v_sqrt_f32_e32 v68, v68
	s_nop 0
	v_mul_f32_e32 v67, v67, v68
	v_mul_f32_e32 v67, v67, v116
	v_cvt_pk_bf16_f32 v67, v69, v67
	v_lshl_add_u64 v[68:69], s[12:13], 0, v[72:73]
	v_lshl_add_u64 v[68:69], v[68:69], 0, v[168:169]
	global_store_dwordx4 v[68:69], v[64:67], off
	s_nop 1
	s_nop 0
	v_rcp_f32_e32 v60, v60
	s_nop 0
	v_mul_f32_e32 v60, v16, v60
	v_mul_f32_e32 v60, 0x3fb8aa3b, v60
	v_exp_f32_e32 v60, v60
	v_rcp_f32_e32 v56, v56
	v_sub_f32_e32 v64, 1.0, v60
	v_add_f32_e32 v60, 1.0, v60
	v_mul_f32_e32 v60, v64, v60
	s_nop 0
	s_nop 0
	s_nop 0
	s_nop 1
	s_nop 1
	v_sqrt_f32_e32 v60, v60
	s_nop 0
	v_mul_f32_e32 v56, v56, v60
	v_add_f32_e32 v60, v61, v25
	v_mul_f32_e32 v60, 0xbfb8aa3b, v60
	v_exp_f32_e32 v60, v60
	v_mul_f32_e32 v56, v56, v115
	v_cvt_pk_bf16_f32 v56, v64, v56
	v_add_f32_e32 v60, 1.0, v60
	s_nop 0
	v_rcp_f32_e32 v60, v60
	s_nop 0
	v_mul_f32_e32 v60, v17, v60
	v_mul_f32_e32 v60, 0x3fb8aa3b, v60
	v_exp_f32_e32 v60, v60
	v_rcp_f32_e32 v57, v57
	v_sub_f32_e32 v61, 1.0, v60
	v_add_f32_e32 v60, 1.0, v60
	v_mul_f32_e32 v60, v61, v60
	s_nop 0
	s_nop 0
	s_nop 0
	s_nop 1
	s_nop 1
	v_sqrt_f32_e32 v60, v60
	s_nop 0
	v_mul_f32_e32 v57, v57, v60
	v_add_f32_e32 v60, v62, v26
	v_mul_f32_e32 v60, 0xbfb8aa3b, v60
	v_exp_f32_e32 v60, v60
	v_mul_f32_e32 v57, v57, v114
	v_cvt_pk_bf16_f32 v57, v61, v57
	v_add_f32_e32 v60, 1.0, v60
	s_nop 0
	v_rcp_f32_e32 v60, v60
	s_nop 0
	v_mul_f32_e32 v60, v18, v60
	v_mul_f32_e32 v60, 0x3fb8aa3b, v60
	v_exp_f32_e32 v60, v60
	v_rcp_f32_e32 v58, v58
	v_sub_f32_e32 v61, 1.0, v60
	v_add_f32_e32 v60, 1.0, v60
	v_mul_f32_e32 v60, v61, v60
	s_nop 0
	s_nop 0
	s_nop 0
	s_nop 1
	s_nop 1
	v_sqrt_f32_e32 v60, v60
	s_nop 0
	v_mul_f32_e32 v58, v58, v60
	v_add_f32_e32 v60, v63, v27
	v_mul_f32_e32 v60, 0xbfb8aa3b, v60
	v_exp_f32_e32 v60, v60
	v_mul_f32_e32 v58, v58, v113
	v_cvt_pk_bf16_f32 v58, v61, v58
	v_add_f32_e32 v60, 1.0, v60
	s_nop 0
	v_rcp_f32_e32 v60, v60
	s_nop 0
	v_mul_f32_e32 v60, v19, v60
	v_mul_f32_e32 v60, 0x3fb8aa3b, v60
; __device__ __forceinline__ unsigned cvt_pk_bf16(float lo, float hi) { unsigned r; asm volatile("v_cvt_pk_bf16_f32 %0, %1, %2" : "=v"(r) : "v"(lo), "v"(hi)); return r; }
; __device__ __forceinline__ float sigmoidf_(float x) { return 1.f / (1.f + __expf(-x)); }
;     __device__ __forceinline__ void operator()(const f32x4 (&acc)[2][2][4][2], const Unit& u, int wr, int wc, int fr, int fq) const {
;     ...
;                 for (int n = 0; n < 2; ++n) { const size_t off = (size_t)(row0 + ai * 128 + m * 16) * 512 + cb + 4 * n;
;                     const f32x4 uv = ucv[m][n], sp = n ? sp1 : sp0, rb = n ? rb1 : rb0, ib = n ? ib1 : ib0; u32x4 pk;
; #pragma unroll
;                     for (int j = 0; j < 4; ++j) { const float r = sigmoidf_(acc[ai][0][m][n][j] + rb[j]), ig = sigmoidf_(acc[ai][1][m][n][j] + ib[j]);
;                         const float la = sp[j] * r; const float ae = __expf(la); const float om = 1.f - ae; pk[j] = cvt_pk_bf16(om, sqrtf(om * (1.f + ae)) * ig * uv[j]); }
;                     *(u32x4*)(AX + off) = pk; }
	v_exp_f32_e32 v60, v60
	v_rcp_f32_e32 v59, v59
	v_sub_f32_e32 v61, 1.0, v60
	v_add_f32_e32 v60, 1.0, v60
	v_mul_f32_e32 v60, v61, v60
	s_nop 0
	s_nop 0
	s_nop 0
	s_nop 1
	s_nop 1
	v_sqrt_f32_e32 v60, v60
	s_nop 0
	v_mul_f32_e32 v59, v59, v60
	v_mul_f32_e32 v59, v59, v112
	v_cvt_pk_bf16_f32 v59, v61, v59
	global_store_dwordx4 v[68:69], v[56:59], off offset:16
	s_nop 1
	v_lshlrev_b64 v[56:57], 11, v[90:91]
	v_rcp_f32_e32 v52, v52
	s_nop 0
	v_mul_f32_e32 v52, v36, v52
	v_mul_f32_e32 v52, 0x3fb8aa3b, v52
	v_exp_f32_e32 v52, v52
	v_rcp_f32_e32 v48, v48
	v_sub_f32_e32 v58, 1.0, v52
	v_add_f32_e32 v52, 1.0, v52
	v_mul_f32_e32 v52, v58, v52
	s_nop 0
	s_nop 0
	s_nop 0
	s_nop 1
	s_nop 1
	v_sqrt_f32_e32 v52, v52
	s_nop 0
	v_mul_f32_e32 v48, v48, v52
	v_add_f32_e32 v52, v53, v45
	v_mul_f32_e32 v52, 0xbfb8aa3b, v52
	v_exp_f32_e32 v52, v52
	v_mul_f32_e32 v48, v48, v111
	v_cvt_pk_bf16_f32 v48, v58, v48
	v_add_f32_e32 v52, 1.0, v52
	s_nop 0
	v_rcp_f32_e32 v52, v52
	s_nop 0
	v_mul_f32_e32 v52, v37, v52
	v_mul_f32_e32 v52, 0x3fb8aa3b, v52
	v_exp_f32_e32 v52, v52
	v_rcp_f32_e32 v49, v49
	v_sub_f32_e32 v53, 1.0, v52
	v_add_f32_e32 v52, 1.0, v52
	v_mul_f32_e32 v52, v53, v52
	s_nop 0
	s_nop 0
	s_nop 0
	s_nop 1
	s_nop 1
	v_sqrt_f32_e32 v52, v52
	s_nop 0
	v_mul_f32_e32 v49, v49, v52
	v_add_f32_e32 v52, v54, v46
	v_mul_f32_e32 v52, 0xbfb8aa3b, v52
	v_exp_f32_e32 v52, v52
	v_mul_f32_e32 v49, v49, v110
	v_cvt_pk_bf16_f32 v49, v53, v49
	v_add_f32_e32 v52, 1.0, v52
	s_nop 0
	v_rcp_f32_e32 v52, v52
	s_nop 0
	v_mul_f32_e32 v52, v38, v52
	v_mul_f32_e32 v52, 0x3fb8aa3b, v52
	v_exp_f32_e32 v52, v52
	v_rcp_f32_e32 v50, v50
	v_sub_f32_e32 v53, 1.0, v52
	v_add_f32_e32 v52, 1.0, v52
	v_mul_f32_e32 v52, v53, v52
	s_nop 0
	s_nop 0
	s_nop 0
	s_nop 1
	s_nop 1
	v_sqrt_f32_e32 v52, v52
	s_nop 0
	v_mul_f32_e32 v50, v50, v52
	v_add_f32_e32 v52, v55, v47
	v_mul_f32_e32 v52, 0xbfb8aa3b, v52
	v_exp_f32_e32 v52, v52
	v_mul_f32_e32 v50, v50, v109
	v_cvt_pk_bf16_f32 v50, v53, v50
	v_add_f32_e32 v52, 1.0, v52
	s_nop 0
	v_rcp_f32_e32 v52, v52
	s_nop 0
	v_mul_f32_e32 v52, v39, v52
	v_mul_f32_e32 v52, 0x3fb8aa3b, v52
	v_exp_f32_e32 v52, v52
	v_rcp_f32_e32 v51, v51
	v_sub_f32_e32 v53, 1.0, v52
	v_add_f32_e32 v52, 1.0, v52
	v_mul_f32_e32 v52, v53, v52
	s_nop 0
	s_nop 0
	s_nop 0
	s_nop 1
	s_nop 1
	v_sqrt_f32_e32 v52, v52
	s_nop 0
	v_mul_f32_e32 v51, v51, v52
	v_mul_f32_e32 v51, v51, v108
	v_cvt_pk_bf16_f32 v51, v53, v51
	v_lshl_add_u64 v[52:53], s[12:13], 0, v[56:57]
	v_lshl_add_u64 v[52:53], v[52:53], 0, v[168:169]
	global_store_dwordx4 v[52:53], v[48:51], off
	s_nop 1
	s_nop 0
	v_rcp_f32_e32 v32, v32
	s_nop 0
	v_mul_f32_e32 v32, v16, v32
	v_mul_f32_e32 v32, 0x3fb8aa3b, v32
	v_exp_f32_e32 v32, v32
	v_rcp_f32_e32 v28, v28
	v_sub_f32_e32 v48, 1.0, v32
	v_add_f32_e32 v32, 1.0, v32
	v_mul_f32_e32 v32, v48, v32
	s_nop 0
	s_nop 0
	s_nop 0
	s_nop 1
	s_nop 1
	v_sqrt_f32_e32 v32, v32
	s_nop 0
	v_mul_f32_e32 v28, v28, v32
	v_add_f32_e32 v32, v33, v25
	v_mul_f32_e32 v32, 0xbfb8aa3b, v32
	v_exp_f32_e32 v32, v32
	v_mul_f32_e32 v28, v28, v107
	v_cvt_pk_bf16_f32 v28, v48, v28
	v_add_f32_e32 v32, 1.0, v32
	s_nop 0
	v_rcp_f32_e32 v32, v32
	s_nop 0
	v_mul_f32_e32 v32, v17, v32
	v_mul_f32_e32 v32, 0x3fb8aa3b, v32
	v_exp_f32_e32 v32, v32
	v_rcp_f32_e32 v29, v29
	v_sub_f32_e32 v33, 1.0, v32
	v_add_f32_e32 v32, 1.0, v32
	v_mul_f32_e32 v32, v33, v32
	s_nop 0
	s_nop 0
	s_nop 0
	s_nop 1
	s_nop 1
	v_sqrt_f32_e32 v32, v32
	s_nop 0
	v_mul_f32_e32 v29, v29, v32
	v_add_f32_e32 v32, v34, v26
	v_mul_f32_e32 v32, 0xbfb8aa3b, v32
	v_exp_f32_e32 v32, v32
	v_mul_f32_e32 v29, v29, v106
	v_cvt_pk_bf16_f32 v29, v33, v29
	v_add_f32_e32 v32, 1.0, v32
	s_nop 0
	v_rcp_f32_e32 v32, v32
	s_nop 0
	v_mul_f32_e32 v32, v18, v32
	v_mul_f32_e32 v32, 0x3fb8aa3b, v32
	v_exp_f32_e32 v32, v32
	v_rcp_f32_e32 v30, v30
	v_sub_f32_e32 v33, 1.0, v32
	v_add_f32_e32 v32, 1.0, v32
	v_mul_f32_e32 v32, v33, v32
	s_nop 0
	s_nop 0
	s_nop 0
	s_nop 1
	s_nop 1
	v_sqrt_f32_e32 v32, v32
	s_nop 0
	v_mul_f32_e32 v30, v30, v32
	v_add_f32_e32 v32, v35, v27
	v_mul_f32_e32 v32, 0xbfb8aa3b, v32
	v_exp_f32_e32 v32, v32
	v_mul_f32_e32 v30, v30, v105
	v_cvt_pk_bf16_f32 v30, v33, v30
	v_add_f32_e32 v32, 1.0, v32
	s_nop 0
	v_rcp_f32_e32 v32, v32
	s_nop 0
	v_mul_f32_e32 v32, v19, v32
	v_mul_f32_e32 v32, 0x3fb8aa3b, v32
	v_exp_f32_e32 v32, v32
	v_rcp_f32_e32 v31, v31
	v_sub_f32_e32 v33, 1.0, v32
	v_add_f32_e32 v32, 1.0, v32
	v_mul_f32_e32 v32, v33, v32
	s_nop 0
	s_nop 0
	s_nop 0
	s_nop 1
	s_nop 1
; __device__ __forceinline__ unsigned cvt_pk_bf16(float lo, float hi) { unsigned r; asm volatile("v_cvt_pk_bf16_f32 %0, %1, %2" : "=v"(r) : "v"(lo), "v"(hi)); return r; }
; __device__ __forceinline__ float sigmoidf_(float x) { return 1.f / (1.f + __expf(-x)); }
;     __device__ __forceinline__ void operator()(const f32x4 (&acc)[2][2][4][2], const Unit& u, int wr, int wc, int fr, int fq) const {
;     ...
;                     const f32x4 uv = ucv[m][n], sp = n ? sp1 : sp0, rb = n ? rb1 : rb0, ib = n ? ib1 : ib0; u32x4 pk;
; #pragma unroll
;                     for (int j = 0; j < 4; ++j) { const float r = sigmoidf_(acc[ai][0][m][n][j] + rb[j]), ig = sigmoidf_(acc[ai][1][m][n][j] + ib[j]);
;                         const float la = sp[j] * r; const float ae = __expf(la); const float om = 1.f - ae; pk[j] = cvt_pk_bf16(om, sqrtf(om * (1.f + ae)) * ig * uv[j]); }
;                     *(u32x4*)(AX + off) = pk; }
	v_sqrt_f32_e32 v32, v32
	s_nop 0
	v_mul_f32_e32 v31, v31, v32
	v_mul_f32_e32 v31, v31, v104
	v_cvt_pk_bf16_f32 v31, v33, v31
	global_store_dwordx4 v[52:53], v[28:31], off offset:16
	s_nop 1
	v_lshlrev_b64 v[28:29], 11, v[88:89]
	v_rcp_f32_e32 v12, v12
	s_nop 0
	v_mul_f32_e32 v12, v36, v12
	v_mul_f32_e32 v12, 0x3fb8aa3b, v12
	v_exp_f32_e32 v12, v12
	v_rcp_f32_e32 v8, v8
	v_sub_f32_e32 v30, 1.0, v12
	v_add_f32_e32 v12, 1.0, v12
	v_mul_f32_e32 v12, v30, v12
	s_nop 0
	s_nop 0
	s_nop 0
	s_nop 1
	s_nop 1
	v_sqrt_f32_e32 v12, v12
	s_nop 0
	v_mul_f32_e32 v8, v8, v12
	v_add_f32_e32 v12, v13, v45
	v_mul_f32_e32 v12, 0xbfb8aa3b, v12
	v_exp_f32_e32 v12, v12
	v_mul_f32_e32 v8, v8, v103
	v_cvt_pk_bf16_f32 v8, v30, v8
	v_add_f32_e32 v12, 1.0, v12
	s_nop 0
	v_rcp_f32_e32 v12, v12
	s_nop 0
	v_mul_f32_e32 v12, v37, v12
	v_mul_f32_e32 v12, 0x3fb8aa3b, v12
	v_exp_f32_e32 v12, v12
	v_rcp_f32_e32 v9, v9
	v_sub_f32_e32 v13, 1.0, v12
	v_add_f32_e32 v12, 1.0, v12
	v_mul_f32_e32 v12, v13, v12
	s_nop 0
	s_nop 0
	s_nop 0
	s_nop 1
	s_nop 1
	v_sqrt_f32_e32 v12, v12
	s_nop 0
	v_mul_f32_e32 v9, v9, v12
	v_add_f32_e32 v12, v14, v46
	v_mul_f32_e32 v12, 0xbfb8aa3b, v12
	v_exp_f32_e32 v12, v12
	v_mul_f32_e32 v9, v9, v102
	v_cvt_pk_bf16_f32 v9, v13, v9
	v_add_f32_e32 v12, 1.0, v12
	s_nop 0
	v_rcp_f32_e32 v12, v12
	s_nop 0
	v_mul_f32_e32 v12, v38, v12
	v_mul_f32_e32 v12, 0x3fb8aa3b, v12
	v_exp_f32_e32 v12, v12
	v_rcp_f32_e32 v10, v10
	v_sub_f32_e32 v13, 1.0, v12
	v_add_f32_e32 v12, 1.0, v12
	v_mul_f32_e32 v12, v13, v12
	s_nop 0
	s_nop 0
	s_nop 0
	s_nop 1
	s_nop 1
	v_sqrt_f32_e32 v12, v12
	s_nop 0
	v_mul_f32_e32 v10, v10, v12
	v_add_f32_e32 v12, v15, v47
	v_mul_f32_e32 v12, 0xbfb8aa3b, v12
	v_exp_f32_e32 v12, v12
	v_mul_f32_e32 v10, v10, v101
	v_cvt_pk_bf16_f32 v10, v13, v10
	v_add_f32_e32 v12, 1.0, v12
	s_nop 0
	v_rcp_f32_e32 v12, v12
	s_nop 0
	v_mul_f32_e32 v12, v39, v12
	v_mul_f32_e32 v12, 0x3fb8aa3b, v12
	v_exp_f32_e32 v12, v12
	v_rcp_f32_e32 v11, v11
	v_sub_f32_e32 v13, 1.0, v12
	v_add_f32_e32 v12, 1.0, v12
	v_mul_f32_e32 v12, v13, v12
	s_nop 0
	s_nop 0
	s_nop 0
	s_nop 1
	s_nop 1
	v_sqrt_f32_e32 v12, v12
	s_nop 0
	v_mul_f32_e32 v11, v11, v12
	v_mul_f32_e32 v11, v11, v100
	v_cvt_pk_bf16_f32 v11, v13, v11
	v_lshl_add_u64 v[12:13], s[12:13], 0, v[28:29]
	v_lshl_add_u64 v[12:13], v[12:13], 0, v[168:169]
	global_store_dwordx4 v[12:13], v[8:11], off
	s_nop 1
	s_nop 0
	v_rcp_f32_e32 v4, v4
	s_nop 0
	v_mul_f32_e32 v4, v16, v4
	v_mul_f32_e32 v4, 0x3fb8aa3b, v4
	v_exp_f32_e32 v4, v4
	v_rcp_f32_e32 v0, v0
	v_sub_f32_e32 v8, 1.0, v4
	v_add_f32_e32 v4, 1.0, v4
	v_mul_f32_e32 v4, v8, v4
	s_nop 0
	s_nop 0
	s_nop 0
	s_nop 1
	s_nop 1
	v_sqrt_f32_e32 v4, v4
	s_nop 0
	v_mul_f32_e32 v0, v0, v4
	v_add_f32_e32 v4, v5, v25
	v_mul_f32_e32 v4, 0xbfb8aa3b, v4
	v_exp_f32_e32 v4, v4
	v_mul_f32_e32 v0, v0, v99
	v_cvt_pk_bf16_f32 v0, v8, v0
	v_add_f32_e32 v4, 1.0, v4
	s_nop 0
	v_rcp_f32_e32 v4, v4
	s_nop 0
	v_mul_f32_e32 v4, v17, v4
	v_mul_f32_e32 v4, 0x3fb8aa3b, v4
	v_exp_f32_e32 v4, v4
	v_rcp_f32_e32 v1, v1
	v_sub_f32_e32 v5, 1.0, v4
	v_add_f32_e32 v4, 1.0, v4
	v_mul_f32_e32 v4, v5, v4
	s_nop 0
	s_nop 0
	s_nop 0
	s_nop 1
	s_nop 1
	v_sqrt_f32_e32 v4, v4
	s_nop 0
	v_mul_f32_e32 v1, v1, v4
	v_add_f32_e32 v4, v6, v26
	v_mul_f32_e32 v4, 0xbfb8aa3b, v4
	v_exp_f32_e32 v4, v4
	v_mul_f32_e32 v1, v1, v98
	v_cvt_pk_bf16_f32 v1, v5, v1
	v_add_f32_e32 v4, 1.0, v4
	s_nop 0
	v_rcp_f32_e32 v4, v4
	s_nop 0
	v_mul_f32_e32 v4, v18, v4
	v_mul_f32_e32 v4, 0x3fb8aa3b, v4
	v_exp_f32_e32 v4, v4
	v_rcp_f32_e32 v2, v2
	v_sub_f32_e32 v5, 1.0, v4
	v_add_f32_e32 v4, 1.0, v4
	v_mul_f32_e32 v4, v5, v4
	s_nop 0
	s_nop 0
	s_nop 0
	s_nop 1
	s_nop 1
	v_sqrt_f32_e32 v4, v4
	s_nop 0
	v_mul_f32_e32 v2, v2, v4
	v_add_f32_e32 v4, v7, v27
	v_mul_f32_e32 v4, 0xbfb8aa3b, v4
	v_exp_f32_e32 v4, v4
	v_mul_f32_e32 v2, v2, v97
	v_cvt_pk_bf16_f32 v2, v5, v2
	v_add_f32_e32 v4, 1.0, v4
	s_nop 0
	v_rcp_f32_e32 v4, v4
	s_nop 0
	v_mul_f32_e32 v4, v19, v4
	v_mul_f32_e32 v4, 0x3fb8aa3b, v4
	v_exp_f32_e32 v4, v4
	v_rcp_f32_e32 v3, v3
	v_sub_f32_e32 v5, 1.0, v4
	v_add_f32_e32 v4, 1.0, v4
	v_mul_f32_e32 v4, v5, v4
	s_nop 0
	s_nop 0
	s_nop 0
	s_nop 1
	s_mov_b64 s[0:1], -1
	s_nop 0
	v_sqrt_f32_e32 v4, v4
	s_nop 0
	v_mul_f32_e32 v3, v3, v4
	v_mul_f32_e32 v3, v3, v96
	v_cvt_pk_bf16_f32 v3, v5, v3
	global_store_dwordx4 v[12:13], v[0:3], off offset:16
	s_and_b64 vcc, exec, s[2:3]
	s_cbranch_vccnz .LBB0_549
	s_andn2_b64 vcc, exec, s[8:9]
	s_cbranch_vccnz .LBB0_548
	s_barrier
	s_branch .LBB0_548
